# latent attention: waves 4-7 run half a key tile behind waves 0-3 (their QK^T beside the partners' softmax/PV), scores kept in registers across the barrier
# speedup vs baseline: 1.0037x; 1.0005x over previous
; DEV void attn_item(const Params& p, int bl, int head, int q0, int nkeys, char* smem, int tid) {
;     ...
;   for (int i = 0; i < 3; ++i) { int c = i * 512 + tid; koff[i] = (c / 12) * KROW + (c % 12) * 16; }
; #pragma unroll
;   for (int i = 0; i < 2; ++i) { int c = i * 512 + tid; voffg[i] = (c >> 4) * NTOK + (c & 15) * 8; voffl[i] = (c >> 4) * VROW + (c & 15) * 16; }
;   __syncthreads();
; #pragma unroll
;   for (int i = 0; i < 3; ++i) kr[i] = *(const u32x4*)(Kg + (long)(i * 512 + tid) * 8);
; #pragma unroll
;   for (int i = 0; i < 2; ++i) vr[i] = *(const u32x4*)(Vg + voffg[i]);
; #pragma unroll
;   for (int i = 0; i < 3; ++i) *(u32x4*)(smem + koff[i]) = kr[i];
; #pragma unroll
;   for (int i = 0; i < 2; ++i) *(u32x4*)(smem + KBYTES + voffl[i]) = vr[i];
;   __syncthreads();
;   f32x4 negm[2];
;   {
;     f32x4 s0[8][2];
; #pragma unroll
;     for (int kf = 0; kf < 8; ++kf) {
;       s0[kf][0] = f32x4{0.f, 0.f, 0.f, 0.f};
;       s0[kf][1] = f32x4{0.f, 0.f, 0.f, 0.f};
; #pragma unroll
;       for (int ks = 0; ks < 3; ++ks) {
;         bf16x8 a = *(const bf16x8*)(smem + (kf * 16 + fr) * KROW + ks * 64 + fq * 16);
;         s0[kf][0] = __builtin_amdgcn_mfma_f32_16x16x32_bf16(a, qf[0][ks], s0[kf][0], 0, 0, 0);
;         s0[kf][1] = __builtin_amdgcn_mfma_f32_16x16x32_bf16(a, qf[1][ks], s0[kf][1], 0, 0, 0);
;       }
;     }
; #pragma unroll
;     for (int qt = 0; qt < 2; ++qt) {
;       float mx = -1e30f;
; #pragma unroll
;       for (int kf = 0; kf < 8; ++kf) mx = fmaxf(fmaxf(fmaxf(s0[kf][qt][0], s0[kf][qt][1]), fmaxf(s0[kf][qt][2], s0[kf][qt][3])), mx);
;       mx = fmaxf(mx, shx(mx, 16, lane));
;       mx = fmaxf(mx, shx(mx, 32, lane));
;       negm[qt] = f32x4{-mx, -mx, -mx, -mx};
;     }
;   }
;   f32x4 lacc[2] = {f32x4{0.f, 0.f, 0.f, 0.f}, f32x4{0.f, 0.f, 0.f, 0.f}};
;   const bf16x8 ones = {0x3F80, 0x3F80, 0x3F80, 0x3F80, 0x3F80, 0x3F80, 0x3F80, 0x3F80};
;   for (int t = 0; t < nt; ++t) {
;     if (t + 1 < nt) {
; #pragma unroll
;       for (int i = 0; i < 3; ++i) kr[i] = *(const u32x4*)(Kg + (long)(t + 1) * 128 * 96 + (long)(i * 512 + tid) * 8);
; #pragma unroll
;       for (int i = 0; i < 2; ++i) vr[i] = *(const u32x4*)(Vg + (t + 1) * 128 + voffg[i]);
;     }
;     const char* kb = smem + (t & 1) * ASTG;
;     const char* vb = kb + KBYTES;
; #pragma unroll
;     for (int hh = 0; hh < 2; ++hh) {
;       f32x4 s[4][2];
; #pragma unroll
.LBB0_990:
	s_mov_b32 s77, s76
	s_mov_b32 s78, s76
	s_mov_b32 s79, s76
	v_mov_b32_e32 v152, s76
	v_mov_b32_e32 v153, s76
	v_mov_b32_e32 v154, s76
	v_mov_b32_e32 v155, s76
	s_mov_b32 s12, 0
	s_mov_b32 s9, 0xb400
	s_mov_b32 s15, 0x16800
	s_mov_b32 s16, 0x6000
	s_mov_b32 s17, 0
	s_mov_b32 s13, 0
	v_mul_u32_u24_e32 v181, 0xe0, v175
	s_mov_b32 s18, 0x15555556
	v_mov_b32_e32 v189, v197
	v_mul_hi_u32 v190, v189, s18
	v_lshlrev_b32_e32 v189, 4, v189
	v_lshl_add_u32 v190, v190, 5, v189
	v_add_u32_e32 v189, 512, v197
	v_mul_hi_u32 v191, v189, s18
	v_lshlrev_b32_e32 v189, 4, v189
	v_lshl_add_u32 v191, v191, 5, v189
	v_add_u32_e32 v189, 1024, v197
	v_mul_hi_u32 v192, v189, s18
	v_lshlrev_b32_e32 v189, 4, v189
	v_lshl_add_u32 v192, v192, 5, v189
	v_readfirstlane_b32 s18, v197
	s_cmpk_ge_u32 s18, 0x100
	s_cbranch_scc1 .Lattn_b_pre
	global_load_dwordx4 v[230:233], v[164:165], off
	global_load_dwordx4 v[234:237], v[166:167], off
	global_load_dwordx4 v[238:241], v[168:169], off
	global_load_dwordx4 v[242:245], v[170:171], off
	global_load_dwordx4 v[246:249], v[172:173], off
	v_lshl_add_u64 v[164:165], v[164:165], 0, s[26:27]
	v_lshl_add_u64 v[166:167], v[166:167], 0, s[26:27]
	v_lshl_add_u64 v[168:169], v[168:169], 0, s[16:17]
	v_lshl_add_u64 v[170:171], v[170:171], 0, s[16:17]
	v_lshl_add_u64 v[172:173], v[172:173], 0, s[16:17]
	v_add_u32_e32 v184, s9, v190
	v_add_u32_e32 v185, s9, v191
	v_add_u32_e32 v186, s9, v192
	v_add_u32_e32 v187, s9, v160
	v_add_u32_e32 v188, s9, v162
	v_add3_u32 v179, s12, v156, v178
	ds_read_b128 v[198:201], v179
	ds_read_b128 v[202:205], v179 offset:3328
	ds_read_b128 v[206:209], v179 offset:6656
	ds_read_b128 v[210:213], v179 offset:9984
	ds_read_b128 v[214:217], v179 offset:64
	ds_read_b128 v[218:221], v179 offset:3392
	ds_read_b128 v[222:225], v179 offset:6720
	ds_read_b128 v[226:229], v179 offset:10048
	s_waitcnt lgkmcnt(7)
	v_mfma_f32_16x16x32_bf16 v[72:75], v[198:201], v[12:15], v[24:27]
	v_mfma_f32_16x16x32_bf16 v[76:79], v[198:201], v[20:23], v[28:31]
	ds_read_b128 v[198:201], v179 offset:128
	s_waitcnt lgkmcnt(7)
	v_mfma_f32_16x16x32_bf16 v[80:83], v[202:205], v[12:15], v[24:27]
	v_mfma_f32_16x16x32_bf16 v[84:87], v[202:205], v[20:23], v[28:31]
	ds_read_b128 v[202:205], v179 offset:3456
	s_waitcnt lgkmcnt(7)
	v_mfma_f32_16x16x32_bf16 v[88:91], v[206:209], v[12:15], v[24:27]
	v_mfma_f32_16x16x32_bf16 v[92:95], v[206:209], v[20:23], v[28:31]
	ds_read_b128 v[206:209], v179 offset:6784
	s_waitcnt lgkmcnt(7)
	v_mfma_f32_16x16x32_bf16 v[96:99], v[210:213], v[12:15], v[24:27]
	v_mfma_f32_16x16x32_bf16 v[100:103], v[210:213], v[20:23], v[28:31]
	ds_read_b128 v[210:213], v179 offset:10112
	s_waitcnt lgkmcnt(7)
	v_mfma_f32_16x16x32_bf16 v[72:75], v[214:217], v[8:11], v[72:75]
	v_mfma_f32_16x16x32_bf16 v[76:79], v[214:217], v[16:19], v[76:79]
	ds_read_b128 v[214:217], v179 offset:13312
	s_waitcnt lgkmcnt(7)
	v_mfma_f32_16x16x32_bf16 v[80:83], v[218:221], v[8:11], v[80:83]
	v_mfma_f32_16x16x32_bf16 v[84:87], v[218:221], v[16:19], v[84:87]
	ds_read_b128 v[218:221], v179 offset:16640
	s_waitcnt lgkmcnt(7)
	v_mfma_f32_16x16x32_bf16 v[88:91], v[222:225], v[8:11], v[88:91]
	v_mfma_f32_16x16x32_bf16 v[92:95], v[222:225], v[16:19], v[92:95]
	ds_read_b128 v[222:225], v179 offset:19968
	s_waitcnt lgkmcnt(7)
	v_mfma_f32_16x16x32_bf16 v[96:99], v[226:229], v[8:11], v[96:99]
	v_mfma_f32_16x16x32_bf16 v[100:103], v[226:229], v[16:19], v[100:103]
	ds_read_b128 v[226:229], v179 offset:23296
	s_waitcnt lgkmcnt(7)
	v_mfma_f32_16x16x32_bf16 v[72:75], v[198:201], v[4:7], v[72:75]
	v_mfma_f32_16x16x32_bf16 v[76:79], v[198:201], v[0:3], v[76:79]
	ds_read_b128 v[198:201], v179 offset:13376
	s_waitcnt lgkmcnt(7)
	v_mfma_f32_16x16x32_bf16 v[80:83], v[202:205], v[4:7], v[80:83]
	v_mfma_f32_16x16x32_bf16 v[84:87], v[202:205], v[0:3], v[84:87]
	ds_read_b128 v[202:205], v179 offset:16704
	s_waitcnt lgkmcnt(7)
	v_mfma_f32_16x16x32_bf16 v[88:91], v[206:209], v[4:7], v[88:91]
	v_mfma_f32_16x16x32_bf16 v[92:95], v[206:209], v[0:3], v[92:95]
	ds_read_b128 v[206:209], v179 offset:20032
	s_waitcnt lgkmcnt(7)
	v_mfma_f32_16x16x32_bf16 v[96:99], v[210:213], v[4:7], v[96:99]
	v_mfma_f32_16x16x32_bf16 v[100:103], v[210:213], v[0:3], v[100:103]
	ds_read_b128 v[210:213], v179 offset:23360
	s_waitcnt lgkmcnt(7)
	v_mfma_f32_16x16x32_bf16 v[104:107], v[214:217], v[12:15], v[24:27]
	v_mfma_f32_16x16x32_bf16 v[108:111], v[214:217], v[20:23], v[28:31]
	ds_read_b128 v[214:217], v179 offset:13440
	s_waitcnt lgkmcnt(7)
	v_mfma_f32_16x16x32_bf16 v[112:115], v[218:221], v[12:15], v[24:27]
	v_mfma_f32_16x16x32_bf16 v[116:119], v[218:221], v[20:23], v[28:31]
	ds_read_b128 v[218:221], v179 offset:16768
	s_waitcnt lgkmcnt(7)
	v_mfma_f32_16x16x32_bf16 v[120:123], v[222:225], v[12:15], v[24:27]
	v_exp_f32_e32 v72, v72
	v_mfma_f32_16x16x32_bf16 v[124:127], v[222:225], v[20:23], v[28:31]
	v_exp_f32_e32 v73, v73
	ds_read_b128 v[222:225], v179 offset:20096
	s_waitcnt lgkmcnt(7)
	v_mfma_f32_16x16x32_bf16 v[128:131], v[226:229], v[12:15], v[24:27]
	v_exp_f32_e32 v74, v74
	v_mfma_f32_16x16x32_bf16 v[132:135], v[226:229], v[20:23], v[28:31]
	v_exp_f32_e32 v75, v75
	ds_read_b128 v[226:229], v179 offset:23424
	s_waitcnt lgkmcnt(7)
	v_mfma_f32_16x16x32_bf16 v[104:107], v[198:201], v[8:11], v[104:107]
	v_exp_f32_e32 v80, v80
	v_exp_f32_e32 v81, v81
	v_mfma_f32_16x16x32_bf16 v[108:111], v[198:201], v[16:19], v[108:111]
	v_exp_f32_e32 v82, v82
	s_waitcnt lgkmcnt(6)
	v_mfma_f32_16x16x32_bf16 v[112:115], v[202:205], v[8:11], v[112:115]
	v_exp_f32_e32 v83, v83
	v_mfma_f32_16x16x32_bf16 v[116:119], v[202:205], v[16:19], v[116:119]
	v_exp_f32_e32 v76, v76
	s_waitcnt lgkmcnt(5)
; DEV float ex2(float x) { return __builtin_amdgcn_exp2f(x); }
; DEV void attn_item(const Params& p, int bl, int head, int q0, int nkeys, char* smem, int tid) {
;     ...
;     for (int hh = 0; hh < 2; ++hh) {
;       f32x4 s[4][2];
; #pragma unroll
;       for (int kf = 0; kf < 4; ++kf) {
; #pragma unroll
;         for (int ks = 0; ks < 3; ++ks) {
;           bf16x8 a = *(const bf16x8*)(kb + (hh * 64 + kf * 16 + fr) * KROW + ks * 64 + fq * 16);
;           s[kf][0] = __builtin_amdgcn_mfma_f32_16x16x32_bf16(a, qf[0][ks], ks == 0 ? negm[0] : s[kf][0], 0, 0, 0);
;           s[kf][1] = __builtin_amdgcn_mfma_f32_16x16x32_bf16(a, qf[1][ks], ks == 0 ? negm[1] : s[kf][1], 0, 0, 0);
;         }
;       }
; #pragma unroll
;       for (int kk = 0; kk < 2; ++kk) {
;         bf16x8 pb[2];
; #pragma unroll
;         for (int qt = 0; qt < 2; ++qt) {
;           const float e0 = ex2(s[2 * kk][qt][0]), e1 = ex2(s[2 * kk][qt][1]), e2 = ex2(s[2 * kk][qt][2]), e3 = ex2(s[2 * kk][qt][3]);
;           const float e4 = ex2(s[2 * kk + 1][qt][0]), e5 = ex2(s[2 * kk + 1][qt][1]), e6 = ex2(s[2 * kk + 1][qt][2]), e7 = ex2(s[2 * kk + 1][qt][3]);
;           u32x4 cw = {pack2(e0, e1), pack2(e2, e3), pack2(e4, e5), pack2(e6, e7)};
;           pb[qt] = __builtin_bit_cast(bf16x8, cw);
;         }
;         lacc[0] = __builtin_amdgcn_mfma_f32_16x16x32_bf16(ones, pb[0], lacc[0], 0, 0, 0);
;         lacc[1] = __builtin_amdgcn_mfma_f32_16x16x32_bf16(ones, pb[1], lacc[1], 0, 0, 0);
; #pragma unroll
;         for (int dvf = 0; dvf < 4; ++dvf) {
;           const char* vp = vb + (dvf * 16 + fr) * VROW + (hh * 64 + kk * 32 + fq * 4) * 2;
;           const uint2 h0 = *(const uint2*)vp, h1 = *(const uint2*)(vp + 32);
;           u32x4 vw = {h0.x, h0.y, h1.x, h1.y};
;           const bf16x8 va = __builtin_bit_cast(bf16x8, vw);
;           o[dvf][0] = __builtin_amdgcn_mfma_f32_16x16x32_bf16(va, pb[0], o[dvf][0], 0, 0, 0);
;           o[dvf][1] = __builtin_amdgcn_mfma_f32_16x16x32_bf16(va, pb[1], o[dvf][1], 0, 0, 0);
;         }
	v_mfma_f32_16x16x32_bf16 v[120:123], v[206:209], v[8:11], v[120:123]
	v_exp_f32_e32 v77, v77
	v_mfma_f32_16x16x32_bf16 v[124:127], v[206:209], v[16:19], v[124:127]
	v_exp_f32_e32 v78, v78
	v_exp_f32_e32 v79, v79
	s_waitcnt lgkmcnt(4)
	v_mfma_f32_16x16x32_bf16 v[128:131], v[210:213], v[8:11], v[128:131]
	v_exp_f32_e32 v84, v84
	v_mfma_f32_16x16x32_bf16 v[132:135], v[210:213], v[16:19], v[132:135]
	v_exp_f32_e32 v85, v85
	s_waitcnt lgkmcnt(3)
	v_mfma_f32_16x16x32_bf16 v[104:107], v[214:217], v[4:7], v[104:107]
	v_exp_f32_e32 v86, v86
	v_mfma_f32_16x16x32_bf16 v[108:111], v[214:217], v[0:3], v[108:111]
	v_exp_f32_e32 v87, v87
	s_waitcnt lgkmcnt(2)
	v_mfma_f32_16x16x32_bf16 v[112:115], v[218:221], v[4:7], v[112:115]
	v_cvt_pk_bf16_f32 v136, v72, v73
	v_cvt_pk_bf16_f32 v137, v74, v75
	v_mfma_f32_16x16x32_bf16 v[116:119], v[218:221], v[0:3], v[116:119]
	v_cvt_pk_bf16_f32 v138, v80, v81
	s_waitcnt lgkmcnt(1)
	v_mfma_f32_16x16x32_bf16 v[120:123], v[222:225], v[4:7], v[120:123]
	v_cvt_pk_bf16_f32 v139, v82, v83
	v_mfma_f32_16x16x32_bf16 v[124:127], v[222:225], v[0:3], v[124:127]
	v_cvt_pk_bf16_f32 v140, v76, v77
	s_waitcnt lgkmcnt(0)
	v_mfma_f32_16x16x32_bf16 v[128:131], v[226:229], v[4:7], v[128:131]
	v_cvt_pk_bf16_f32 v141, v78, v79
	v_mfma_f32_16x16x32_bf16 v[132:135], v[226:229], v[0:3], v[132:135]
	v_cvt_pk_bf16_f32 v142, v84, v85
	v_cvt_pk_bf16_f32 v143, v86, v87
	s_waitcnt vmcnt(0)
	ds_write_b128 v184, v[238:241]
	ds_write_b128 v185, v[242:245]
	ds_write_b128 v186, v[246:249]
	ds_write_b128 v187, v[230:233] offset:28672
	ds_write_b128 v188, v[234:237] offset:28672
	v_add3_u32 v180, s12, v176, v177
	ds_read_b64 v[198:199], v180 offset:26624
	ds_read_b64 v[200:201], v180 offset:26656
	ds_read_b64 v[202:203], v180 offset:30976
	ds_read_b64 v[204:205], v180 offset:31008
	ds_read_b64 v[206:207], v180 offset:35328
	ds_read_b64 v[208:209], v180 offset:35360
	ds_read_b64 v[210:211], v180 offset:39680
	ds_read_b64 v[212:213], v180 offset:39712
	ds_read_b64 v[214:215], v180 offset:26688
	ds_read_b64 v[216:217], v180 offset:26720
	ds_read_b64 v[218:219], v180 offset:31040
	ds_read_b64 v[220:221], v180 offset:31072
	ds_read_b64 v[222:223], v180 offset:35392
	ds_read_b64 v[224:225], v180 offset:35424
	ds_read_b64 v[226:227], v180 offset:39744
	ds_read_b64 v[228:229], v180 offset:39776
	v_mfma_f32_16x16x32_bf16 v[68:71], v[152:155], v[136:139], v[68:71]
	v_exp_f32_e32 v88, v88
	v_exp_f32_e32 v89, v89
	v_mfma_f32_16x16x32_bf16 v[56:59], v[152:155], v[140:143], v[56:59]
	v_exp_f32_e32 v90, v90
	v_exp_f32_e32 v91, v91
	s_waitcnt lgkmcnt(8)
	v_mfma_f32_16x16x32_bf16 v[32:35], v[198:201], v[136:139], v[32:35]
	v_exp_f32_e32 v96, v96
	v_exp_f32_e32 v97, v97
	v_mfma_f32_16x16x32_bf16 v[36:39], v[198:201], v[140:143], v[36:39]
	v_exp_f32_e32 v98, v98
	v_exp_f32_e32 v99, v99
	v_exp_f32_e32 v92, v92
	v_mfma_f32_16x16x32_bf16 v[40:43], v[202:205], v[136:139], v[40:43]
	v_exp_f32_e32 v93, v93
	v_exp_f32_e32 v94, v94
	v_mfma_f32_16x16x32_bf16 v[60:63], v[202:205], v[140:143], v[60:63]
	v_exp_f32_e32 v95, v95
	v_exp_f32_e32 v100, v100
	v_exp_f32_e32 v101, v101
	v_mfma_f32_16x16x32_bf16 v[44:47], v[206:209], v[136:139], v[44:47]
	v_exp_f32_e32 v102, v102
	v_exp_f32_e32 v103, v103
	v_mfma_f32_16x16x32_bf16 v[64:67], v[206:209], v[140:143], v[64:67]
	v_cvt_pk_bf16_f32 v144, v88, v89
	v_cvt_pk_bf16_f32 v145, v90, v91
	v_cvt_pk_bf16_f32 v146, v96, v97
	v_mfma_f32_16x16x32_bf16 v[48:51], v[210:213], v[136:139], v[48:51]
	v_cvt_pk_bf16_f32 v147, v98, v99
	v_cvt_pk_bf16_f32 v148, v92, v93
	v_mfma_f32_16x16x32_bf16 v[52:55], v[210:213], v[140:143], v[52:55]
	v_cvt_pk_bf16_f32 v149, v94, v95
	v_cvt_pk_bf16_f32 v150, v100, v101
	v_cvt_pk_bf16_f32 v151, v102, v103
	ds_read_b64 v[198:199], v180 offset:26752
	ds_read_b64 v[200:201], v180 offset:26784
	ds_read_b64 v[202:203], v180 offset:31104
	ds_read_b64 v[204:205], v180 offset:31136
	ds_read_b64 v[206:207], v180 offset:35456
	ds_read_b64 v[208:209], v180 offset:35488
	ds_read_b64 v[210:211], v180 offset:39808
	ds_read_b64 v[212:213], v180 offset:39840
	s_nop 1
	v_mfma_f32_16x16x32_bf16 v[68:71], v[152:155], v[144:147], v[68:71]
	v_exp_f32_e32 v104, v104
	v_exp_f32_e32 v105, v105
	v_mfma_f32_16x16x32_bf16 v[56:59], v[152:155], v[148:151], v[56:59]
	v_exp_f32_e32 v106, v106
	v_exp_f32_e32 v107, v107
	s_waitcnt lgkmcnt(8)
	v_mfma_f32_16x16x32_bf16 v[32:35], v[214:217], v[144:147], v[32:35]
	v_exp_f32_e32 v112, v112
	v_exp_f32_e32 v113, v113
	v_mfma_f32_16x16x32_bf16 v[36:39], v[214:217], v[148:151], v[36:39]
	v_exp_f32_e32 v114, v114
	v_exp_f32_e32 v115, v115
	v_exp_f32_e32 v108, v108
	v_mfma_f32_16x16x32_bf16 v[40:43], v[218:221], v[144:147], v[40:43]
	v_exp_f32_e32 v109, v109
	v_exp_f32_e32 v110, v110
	v_mfma_f32_16x16x32_bf16 v[60:63], v[218:221], v[148:151], v[60:63]
	v_exp_f32_e32 v111, v111
	v_exp_f32_e32 v116, v116
	v_exp_f32_e32 v117, v117
	v_mfma_f32_16x16x32_bf16 v[44:47], v[222:225], v[144:147], v[44:47]
	v_exp_f32_e32 v118, v118
	v_exp_f32_e32 v119, v119
	v_mfma_f32_16x16x32_bf16 v[64:67], v[222:225], v[148:151], v[64:67]
	v_cvt_pk_bf16_f32 v136, v104, v105
	v_cvt_pk_bf16_f32 v137, v106, v107
	v_cvt_pk_bf16_f32 v138, v112, v113
	v_mfma_f32_16x16x32_bf16 v[48:51], v[226:229], v[144:147], v[48:51]
	v_cvt_pk_bf16_f32 v139, v114, v115
	v_cvt_pk_bf16_f32 v140, v108, v109
	v_mfma_f32_16x16x32_bf16 v[52:55], v[226:229], v[148:151], v[52:55]
	v_cvt_pk_bf16_f32 v141, v110, v111
	v_cvt_pk_bf16_f32 v142, v116, v117
	v_cvt_pk_bf16_f32 v143, v118, v119
	ds_read_b64 v[214:215], v180 offset:26816
	ds_read_b64 v[216:217], v180 offset:26848
	ds_read_b64 v[218:219], v180 offset:31168
	ds_read_b64 v[220:221], v180 offset:31200
	ds_read_b64 v[222:223], v180 offset:35520
	ds_read_b64 v[224:225], v180 offset:35552
	ds_read_b64 v[226:227], v180 offset:39872
	ds_read_b64 v[228:229], v180 offset:39904
	s_nop 1
	v_mfma_f32_16x16x32_bf16 v[68:71], v[152:155], v[136:139], v[68:71]
	v_exp_f32_e32 v120, v120
	v_exp_f32_e32 v121, v121
	v_mfma_f32_16x16x32_bf16 v[56:59], v[152:155], v[140:143], v[56:59]
	v_exp_f32_e32 v122, v122
	v_exp_f32_e32 v123, v123
	s_waitcnt lgkmcnt(8)
; DEV float ex2(float x) { return __builtin_amdgcn_exp2f(x); }
; DEV void attn_item(const Params& p, int bl, int head, int q0, int nkeys, char* smem, int tid) {
;     ...
;     for (int hh = 0; hh < 2; ++hh) {
;       f32x4 s[4][2];
; #pragma unroll
;       for (int kf = 0; kf < 4; ++kf) {
; #pragma unroll
;         for (int ks = 0; ks < 3; ++ks) {
;           bf16x8 a = *(const bf16x8*)(kb + (hh * 64 + kf * 16 + fr) * KROW + ks * 64 + fq * 16);
;           s[kf][0] = __builtin_amdgcn_mfma_f32_16x16x32_bf16(a, qf[0][ks], ks == 0 ? negm[0] : s[kf][0], 0, 0, 0);
;           s[kf][1] = __builtin_amdgcn_mfma_f32_16x16x32_bf16(a, qf[1][ks], ks == 0 ? negm[1] : s[kf][1], 0, 0, 0);
;         }
;       }
; #pragma unroll
;       for (int kk = 0; kk < 2; ++kk) {
;         bf16x8 pb[2];
; #pragma unroll
;         for (int qt = 0; qt < 2; ++qt) {
;           const float e0 = ex2(s[2 * kk][qt][0]), e1 = ex2(s[2 * kk][qt][1]), e2 = ex2(s[2 * kk][qt][2]), e3 = ex2(s[2 * kk][qt][3]);
;           const float e4 = ex2(s[2 * kk + 1][qt][0]), e5 = ex2(s[2 * kk + 1][qt][1]), e6 = ex2(s[2 * kk + 1][qt][2]), e7 = ex2(s[2 * kk + 1][qt][3]);
;           u32x4 cw = {pack2(e0, e1), pack2(e2, e3), pack2(e4, e5), pack2(e6, e7)};
;           pb[qt] = __builtin_bit_cast(bf16x8, cw);
;         }
;         lacc[0] = __builtin_amdgcn_mfma_f32_16x16x32_bf16(ones, pb[0], lacc[0], 0, 0, 0);
;         lacc[1] = __builtin_amdgcn_mfma_f32_16x16x32_bf16(ones, pb[1], lacc[1], 0, 0, 0);
; #pragma unroll
;         for (int dvf = 0; dvf < 4; ++dvf) {
;           const char* vp = vb + (dvf * 16 + fr) * VROW + (hh * 64 + kk * 32 + fq * 4) * 2;
;           const uint2 h0 = *(const uint2*)vp, h1 = *(const uint2*)(vp + 32);
;           u32x4 vw = {h0.x, h0.y, h1.x, h1.y};
;           const bf16x8 va = __builtin_bit_cast(bf16x8, vw);
;           o[dvf][0] = __builtin_amdgcn_mfma_f32_16x16x32_bf16(va, pb[0], o[dvf][0], 0, 0, 0);
;           o[dvf][1] = __builtin_amdgcn_mfma_f32_16x16x32_bf16(va, pb[1], o[dvf][1], 0, 0, 0);
;         }
;       }
;     }
;     if (t + 1 < nt) {
;       char* nb = smem + ((t + 1) & 1) * ASTG;
; #pragma unroll
;       for (int i = 0; i < 3; ++i) *(u32x4*)(nb + koff[i]) = kr[i];
; #pragma unroll
;       for (int i = 0; i < 2; ++i) *(u32x4*)(nb + KBYTES + voffl[i]) = vr[i];
;     }
;     __syncthreads();
	v_mfma_f32_16x16x32_bf16 v[32:35], v[198:201], v[136:139], v[32:35]
	v_exp_f32_e32 v128, v128
	v_exp_f32_e32 v129, v129
	v_mfma_f32_16x16x32_bf16 v[36:39], v[198:201], v[140:143], v[36:39]
	v_exp_f32_e32 v130, v130
	v_exp_f32_e32 v131, v131
	v_exp_f32_e32 v124, v124
	v_mfma_f32_16x16x32_bf16 v[40:43], v[202:205], v[136:139], v[40:43]
	v_exp_f32_e32 v125, v125
	v_exp_f32_e32 v126, v126
	v_mfma_f32_16x16x32_bf16 v[60:63], v[202:205], v[140:143], v[60:63]
	v_exp_f32_e32 v127, v127
	v_exp_f32_e32 v132, v132
	v_exp_f32_e32 v133, v133
	v_mfma_f32_16x16x32_bf16 v[44:47], v[206:209], v[136:139], v[44:47]
	v_exp_f32_e32 v134, v134
	v_exp_f32_e32 v135, v135
	v_mfma_f32_16x16x32_bf16 v[64:67], v[206:209], v[140:143], v[64:67]
	v_cvt_pk_bf16_f32 v144, v120, v121
	v_cvt_pk_bf16_f32 v145, v122, v123
	v_cvt_pk_bf16_f32 v146, v128, v129
	v_mfma_f32_16x16x32_bf16 v[48:51], v[210:213], v[136:139], v[48:51]
	v_cvt_pk_bf16_f32 v147, v130, v131
	v_cvt_pk_bf16_f32 v148, v124, v125
	v_mfma_f32_16x16x32_bf16 v[52:55], v[210:213], v[140:143], v[52:55]
	v_cvt_pk_bf16_f32 v149, v126, v127
	v_cvt_pk_bf16_f32 v150, v132, v133
	v_cvt_pk_bf16_f32 v151, v134, v135
	s_nop 1
	v_mfma_f32_16x16x32_bf16 v[68:71], v[152:155], v[144:147], v[68:71]
	v_mfma_f32_16x16x32_bf16 v[56:59], v[152:155], v[148:151], v[56:59]
	s_waitcnt lgkmcnt(0)
	v_mfma_f32_16x16x32_bf16 v[32:35], v[214:217], v[144:147], v[32:35]
	v_mfma_f32_16x16x32_bf16 v[36:39], v[214:217], v[148:151], v[36:39]
	v_mfma_f32_16x16x32_bf16 v[40:43], v[218:221], v[144:147], v[40:43]
	v_mfma_f32_16x16x32_bf16 v[60:63], v[218:221], v[148:151], v[60:63]
	v_mfma_f32_16x16x32_bf16 v[44:47], v[222:225], v[144:147], v[44:47]
	v_mfma_f32_16x16x32_bf16 v[64:67], v[222:225], v[148:151], v[64:67]
	v_mfma_f32_16x16x32_bf16 v[48:51], v[226:229], v[144:147], v[48:51]
	v_mfma_f32_16x16x32_bf16 v[52:55], v[226:229], v[148:151], v[52:55]
	s_waitcnt lgkmcnt(0)
	s_barrier
	s_mov_b32 s18, s15
	s_mov_b32 s15, s12
	s_mov_b32 s12, s9
	s_mov_b32 s9, s18
	s_add_i32 s13, s13, 1
.Lattn_a_loop:
	global_load_dwordx4 v[230:233], v[164:165], off
	global_load_dwordx4 v[234:237], v[166:167], off
	global_load_dwordx4 v[238:241], v[168:169], off
	global_load_dwordx4 v[242:245], v[170:171], off
	global_load_dwordx4 v[246:249], v[172:173], off
	v_lshl_add_u64 v[164:165], v[164:165], 0, s[26:27]
	v_lshl_add_u64 v[166:167], v[166:167], 0, s[26:27]
	v_lshl_add_u64 v[168:169], v[168:169], 0, s[16:17]
	v_lshl_add_u64 v[170:171], v[170:171], 0, s[16:17]
	v_lshl_add_u64 v[172:173], v[172:173], 0, s[16:17]
	v_add_u32_e32 v184, s9, v190
	v_add_u32_e32 v185, s9, v191
	v_add_u32_e32 v186, s9, v192
	v_add_u32_e32 v187, s9, v160
	v_add_u32_e32 v188, s9, v162
	v_add3_u32 v179, s12, v156, v181
	ds_read_b128 v[198:201], v179
	ds_read_b128 v[202:205], v179 offset:3584
	ds_read_b128 v[206:209], v179 offset:7168
	ds_read_b128 v[210:213], v179 offset:10752
	ds_read_b128 v[214:217], v179 offset:64
	ds_read_b128 v[218:221], v179 offset:3648
	ds_read_b128 v[222:225], v179 offset:7232
	ds_read_b128 v[226:229], v179 offset:10816
	s_waitcnt lgkmcnt(7)
	v_mfma_f32_16x16x32_bf16 v[72:75], v[198:201], v[12:15], v[24:27]
	v_mfma_f32_16x16x32_bf16 v[76:79], v[198:201], v[20:23], v[28:31]
	ds_read_b128 v[198:201], v179 offset:128
	s_waitcnt lgkmcnt(7)
	v_mfma_f32_16x16x32_bf16 v[80:83], v[202:205], v[12:15], v[24:27]
	v_mfma_f32_16x16x32_bf16 v[84:87], v[202:205], v[20:23], v[28:31]
	ds_read_b128 v[202:205], v179 offset:3712
	s_waitcnt lgkmcnt(7)
	v_mfma_f32_16x16x32_bf16 v[88:91], v[206:209], v[12:15], v[24:27]
	v_mfma_f32_16x16x32_bf16 v[92:95], v[206:209], v[20:23], v[28:31]
	ds_read_b128 v[206:209], v179 offset:7296
	s_waitcnt lgkmcnt(7)
	v_mfma_f32_16x16x32_bf16 v[96:99], v[210:213], v[12:15], v[24:27]
	v_mfma_f32_16x16x32_bf16 v[100:103], v[210:213], v[20:23], v[28:31]
	ds_read_b128 v[210:213], v179 offset:10880
	s_waitcnt lgkmcnt(7)
	v_mfma_f32_16x16x32_bf16 v[72:75], v[214:217], v[8:11], v[72:75]
	v_mfma_f32_16x16x32_bf16 v[76:79], v[214:217], v[16:19], v[76:79]
	ds_read_b128 v[214:217], v179 offset:14336
	s_waitcnt lgkmcnt(7)
	v_mfma_f32_16x16x32_bf16 v[80:83], v[218:221], v[8:11], v[80:83]
	v_mfma_f32_16x16x32_bf16 v[84:87], v[218:221], v[16:19], v[84:87]
	ds_read_b128 v[218:221], v179 offset:17920
	s_waitcnt lgkmcnt(7)
	v_mfma_f32_16x16x32_bf16 v[88:91], v[222:225], v[8:11], v[88:91]
	v_mfma_f32_16x16x32_bf16 v[92:95], v[222:225], v[16:19], v[92:95]
	ds_read_b128 v[222:225], v179 offset:21504
	s_waitcnt lgkmcnt(7)
	v_mfma_f32_16x16x32_bf16 v[96:99], v[226:229], v[8:11], v[96:99]
	v_mfma_f32_16x16x32_bf16 v[100:103], v[226:229], v[16:19], v[100:103]
	ds_read_b128 v[226:229], v179 offset:25088
	s_waitcnt lgkmcnt(7)
	v_mfma_f32_16x16x32_bf16 v[72:75], v[198:201], v[4:7], v[72:75]
	v_mfma_f32_16x16x32_bf16 v[76:79], v[198:201], v[0:3], v[76:79]
	ds_read_b128 v[198:201], v179 offset:14400
	s_waitcnt lgkmcnt(7)
	v_mfma_f32_16x16x32_bf16 v[80:83], v[202:205], v[4:7], v[80:83]
	v_mfma_f32_16x16x32_bf16 v[84:87], v[202:205], v[0:3], v[84:87]
	ds_read_b128 v[202:205], v179 offset:17984
	s_waitcnt lgkmcnt(7)
	v_mfma_f32_16x16x32_bf16 v[88:91], v[206:209], v[4:7], v[88:91]
	v_mfma_f32_16x16x32_bf16 v[92:95], v[206:209], v[0:3], v[92:95]
	ds_read_b128 v[206:209], v179 offset:21568
	s_waitcnt lgkmcnt(7)
	v_mfma_f32_16x16x32_bf16 v[96:99], v[210:213], v[4:7], v[96:99]
	v_mfma_f32_16x16x32_bf16 v[100:103], v[210:213], v[0:3], v[100:103]
	ds_read_b128 v[210:213], v179 offset:25152
	s_waitcnt lgkmcnt(7)
	v_mfma_f32_16x16x32_bf16 v[104:107], v[214:217], v[12:15], v[24:27]
	v_mfma_f32_16x16x32_bf16 v[108:111], v[214:217], v[20:23], v[28:31]
	ds_read_b128 v[214:217], v179 offset:14464
	s_waitcnt lgkmcnt(7)
; DEV float ex2(float x) { return __builtin_amdgcn_exp2f(x); }
; DEV void attn_item(const Params& p, int bl, int head, int q0, int nkeys, char* smem, int tid) {
;     ...
;     for (int hh = 0; hh < 2; ++hh) {
;       f32x4 s[4][2];
; #pragma unroll
;       for (int kf = 0; kf < 4; ++kf) {
; #pragma unroll
;         for (int ks = 0; ks < 3; ++ks) {
;           bf16x8 a = *(const bf16x8*)(kb + (hh * 64 + kf * 16 + fr) * KROW + ks * 64 + fq * 16);
;           s[kf][0] = __builtin_amdgcn_mfma_f32_16x16x32_bf16(a, qf[0][ks], ks == 0 ? negm[0] : s[kf][0], 0, 0, 0);
;           s[kf][1] = __builtin_amdgcn_mfma_f32_16x16x32_bf16(a, qf[1][ks], ks == 0 ? negm[1] : s[kf][1], 0, 0, 0);
;         }
;       }
; #pragma unroll
;       for (int kk = 0; kk < 2; ++kk) {
;         bf16x8 pb[2];
; #pragma unroll
;         for (int qt = 0; qt < 2; ++qt) {
;           const float e0 = ex2(s[2 * kk][qt][0]), e1 = ex2(s[2 * kk][qt][1]), e2 = ex2(s[2 * kk][qt][2]), e3 = ex2(s[2 * kk][qt][3]);
;           const float e4 = ex2(s[2 * kk + 1][qt][0]), e5 = ex2(s[2 * kk + 1][qt][1]), e6 = ex2(s[2 * kk + 1][qt][2]), e7 = ex2(s[2 * kk + 1][qt][3]);
;           u32x4 cw = {pack2(e0, e1), pack2(e2, e3), pack2(e4, e5), pack2(e6, e7)};
;           pb[qt] = __builtin_bit_cast(bf16x8, cw);
;         }
;         lacc[0] = __builtin_amdgcn_mfma_f32_16x16x32_bf16(ones, pb[0], lacc[0], 0, 0, 0);
;         lacc[1] = __builtin_amdgcn_mfma_f32_16x16x32_bf16(ones, pb[1], lacc[1], 0, 0, 0);
; #pragma unroll
;         for (int dvf = 0; dvf < 4; ++dvf) {
;           const char* vp = vb + (dvf * 16 + fr) * VROW + (hh * 64 + kk * 32 + fq * 4) * 2;
;           const uint2 h0 = *(const uint2*)vp, h1 = *(const uint2*)(vp + 32);
;           u32x4 vw = {h0.x, h0.y, h1.x, h1.y};
;           const bf16x8 va = __builtin_bit_cast(bf16x8, vw);
;           o[dvf][0] = __builtin_amdgcn_mfma_f32_16x16x32_bf16(va, pb[0], o[dvf][0], 0, 0, 0);
;           o[dvf][1] = __builtin_amdgcn_mfma_f32_16x16x32_bf16(va, pb[1], o[dvf][1], 0, 0, 0);
;         }
	v_mfma_f32_16x16x32_bf16 v[112:115], v[218:221], v[12:15], v[24:27]
	v_mfma_f32_16x16x32_bf16 v[116:119], v[218:221], v[20:23], v[28:31]
	ds_read_b128 v[218:221], v179 offset:18048
	s_waitcnt lgkmcnt(7)
	v_mfma_f32_16x16x32_bf16 v[120:123], v[222:225], v[12:15], v[24:27]
	v_exp_f32_e32 v72, v72
	v_mfma_f32_16x16x32_bf16 v[124:127], v[222:225], v[20:23], v[28:31]
	v_exp_f32_e32 v73, v73
	ds_read_b128 v[222:225], v179 offset:21632
	s_waitcnt lgkmcnt(7)
	v_mfma_f32_16x16x32_bf16 v[128:131], v[226:229], v[12:15], v[24:27]
	v_exp_f32_e32 v74, v74
	v_mfma_f32_16x16x32_bf16 v[132:135], v[226:229], v[20:23], v[28:31]
	v_exp_f32_e32 v75, v75
	ds_read_b128 v[226:229], v179 offset:25216
	s_waitcnt lgkmcnt(7)
	v_mfma_f32_16x16x32_bf16 v[104:107], v[198:201], v[8:11], v[104:107]
	v_exp_f32_e32 v80, v80
	v_exp_f32_e32 v81, v81
	v_mfma_f32_16x16x32_bf16 v[108:111], v[198:201], v[16:19], v[108:111]
	v_exp_f32_e32 v82, v82
	s_waitcnt lgkmcnt(6)
	v_mfma_f32_16x16x32_bf16 v[112:115], v[202:205], v[8:11], v[112:115]
	v_exp_f32_e32 v83, v83
	v_mfma_f32_16x16x32_bf16 v[116:119], v[202:205], v[16:19], v[116:119]
	v_exp_f32_e32 v76, v76
	s_waitcnt lgkmcnt(5)
	v_mfma_f32_16x16x32_bf16 v[120:123], v[206:209], v[8:11], v[120:123]
	v_exp_f32_e32 v77, v77
	v_mfma_f32_16x16x32_bf16 v[124:127], v[206:209], v[16:19], v[124:127]
	v_exp_f32_e32 v78, v78
	v_exp_f32_e32 v79, v79
	s_waitcnt lgkmcnt(4)
	v_mfma_f32_16x16x32_bf16 v[128:131], v[210:213], v[8:11], v[128:131]
	v_exp_f32_e32 v84, v84
	v_mfma_f32_16x16x32_bf16 v[132:135], v[210:213], v[16:19], v[132:135]
	v_exp_f32_e32 v85, v85
	s_waitcnt lgkmcnt(3)
	v_mfma_f32_16x16x32_bf16 v[104:107], v[214:217], v[4:7], v[104:107]
	v_exp_f32_e32 v86, v86
	v_mfma_f32_16x16x32_bf16 v[108:111], v[214:217], v[0:3], v[108:111]
	v_exp_f32_e32 v87, v87
	s_waitcnt lgkmcnt(2)
	v_mfma_f32_16x16x32_bf16 v[112:115], v[218:221], v[4:7], v[112:115]
	v_cvt_pk_bf16_f32 v136, v72, v73
	v_cvt_pk_bf16_f32 v137, v74, v75
	v_mfma_f32_16x16x32_bf16 v[116:119], v[218:221], v[0:3], v[116:119]
	v_cvt_pk_bf16_f32 v138, v80, v81
	s_waitcnt lgkmcnt(1)
	v_mfma_f32_16x16x32_bf16 v[120:123], v[222:225], v[4:7], v[120:123]
	v_cvt_pk_bf16_f32 v139, v82, v83
	v_mfma_f32_16x16x32_bf16 v[124:127], v[222:225], v[0:3], v[124:127]
	v_cvt_pk_bf16_f32 v140, v76, v77
	s_waitcnt lgkmcnt(0)
	v_mfma_f32_16x16x32_bf16 v[128:131], v[226:229], v[4:7], v[128:131]
	v_cvt_pk_bf16_f32 v141, v78, v79
	v_mfma_f32_16x16x32_bf16 v[132:135], v[226:229], v[0:3], v[132:135]
	v_cvt_pk_bf16_f32 v142, v84, v85
	v_cvt_pk_bf16_f32 v143, v86, v87
	s_waitcnt vmcnt(0)
	ds_write_b128 v184, v[238:241]
	ds_write_b128 v185, v[242:245]
	ds_write_b128 v186, v[246:249]
	ds_write_b128 v187, v[230:233] offset:28672
	ds_write_b128 v188, v[234:237] offset:28672
	v_add3_u32 v180, s12, v176, v177
	ds_read_b64 v[198:199], v180 offset:28672
	ds_read_b64 v[200:201], v180 offset:28704
	ds_read_b64 v[202:203], v180 offset:33024
	ds_read_b64 v[204:205], v180 offset:33056
	ds_read_b64 v[206:207], v180 offset:37376
	ds_read_b64 v[208:209], v180 offset:37408
	ds_read_b64 v[210:211], v180 offset:41728
	ds_read_b64 v[212:213], v180 offset:41760
	ds_read_b64 v[214:215], v180 offset:28736
	ds_read_b64 v[216:217], v180 offset:28768
	ds_read_b64 v[218:219], v180 offset:33088
	ds_read_b64 v[220:221], v180 offset:33120
	ds_read_b64 v[222:223], v180 offset:37440
	ds_read_b64 v[224:225], v180 offset:37472
	ds_read_b64 v[226:227], v180 offset:41792
	ds_read_b64 v[228:229], v180 offset:41824
	v_mfma_f32_16x16x32_bf16 v[68:71], v[152:155], v[136:139], v[68:71]
	v_exp_f32_e32 v88, v88
	v_exp_f32_e32 v89, v89
	v_mfma_f32_16x16x32_bf16 v[56:59], v[152:155], v[140:143], v[56:59]
	v_exp_f32_e32 v90, v90
	v_exp_f32_e32 v91, v91
	s_waitcnt lgkmcnt(8)
	v_mfma_f32_16x16x32_bf16 v[32:35], v[198:201], v[136:139], v[32:35]
	v_exp_f32_e32 v96, v96
	v_exp_f32_e32 v97, v97
	v_mfma_f32_16x16x32_bf16 v[36:39], v[198:201], v[140:143], v[36:39]
	v_exp_f32_e32 v98, v98
	v_exp_f32_e32 v99, v99
	v_exp_f32_e32 v92, v92
	v_mfma_f32_16x16x32_bf16 v[40:43], v[202:205], v[136:139], v[40:43]
	v_exp_f32_e32 v93, v93
	v_exp_f32_e32 v94, v94
	v_mfma_f32_16x16x32_bf16 v[60:63], v[202:205], v[140:143], v[60:63]
	v_exp_f32_e32 v95, v95
	v_exp_f32_e32 v100, v100
	v_exp_f32_e32 v101, v101
	v_mfma_f32_16x16x32_bf16 v[44:47], v[206:209], v[136:139], v[44:47]
	v_exp_f32_e32 v102, v102
	v_exp_f32_e32 v103, v103
	v_mfma_f32_16x16x32_bf16 v[64:67], v[206:209], v[140:143], v[64:67]
	v_cvt_pk_bf16_f32 v144, v88, v89
	v_cvt_pk_bf16_f32 v145, v90, v91
	v_cvt_pk_bf16_f32 v146, v96, v97
	v_mfma_f32_16x16x32_bf16 v[48:51], v[210:213], v[136:139], v[48:51]
	v_cvt_pk_bf16_f32 v147, v98, v99
	v_cvt_pk_bf16_f32 v148, v92, v93
	v_mfma_f32_16x16x32_bf16 v[52:55], v[210:213], v[140:143], v[52:55]
	v_cvt_pk_bf16_f32 v149, v94, v95
	v_cvt_pk_bf16_f32 v150, v100, v101
	v_cvt_pk_bf16_f32 v151, v102, v103
	ds_read_b64 v[198:199], v180 offset:28800
	ds_read_b64 v[200:201], v180 offset:28832
	ds_read_b64 v[202:203], v180 offset:33152
	ds_read_b64 v[204:205], v180 offset:33184
	ds_read_b64 v[206:207], v180 offset:37504
	ds_read_b64 v[208:209], v180 offset:37536
	ds_read_b64 v[210:211], v180 offset:41856
	ds_read_b64 v[212:213], v180 offset:41888
	s_nop 1
	v_mfma_f32_16x16x32_bf16 v[68:71], v[152:155], v[144:147], v[68:71]
	v_exp_f32_e32 v104, v104
	v_exp_f32_e32 v105, v105
	v_mfma_f32_16x16x32_bf16 v[56:59], v[152:155], v[148:151], v[56:59]
	v_exp_f32_e32 v106, v106
	v_exp_f32_e32 v107, v107
	s_waitcnt lgkmcnt(8)
; DEV float ex2(float x) { return __builtin_amdgcn_exp2f(x); }
; DEV void attn_item(const Params& p, int bl, int head, int q0, int nkeys, char* smem, int tid) {
;     ...
;     for (int hh = 0; hh < 2; ++hh) {
;       f32x4 s[4][2];
; #pragma unroll
;       for (int kf = 0; kf < 4; ++kf) {
; #pragma unroll
;         for (int ks = 0; ks < 3; ++ks) {
;           bf16x8 a = *(const bf16x8*)(kb + (hh * 64 + kf * 16 + fr) * KROW + ks * 64 + fq * 16);
;           s[kf][0] = __builtin_amdgcn_mfma_f32_16x16x32_bf16(a, qf[0][ks], ks == 0 ? negm[0] : s[kf][0], 0, 0, 0);
;           s[kf][1] = __builtin_amdgcn_mfma_f32_16x16x32_bf16(a, qf[1][ks], ks == 0 ? negm[1] : s[kf][1], 0, 0, 0);
;         }
;       }
; #pragma unroll
;       for (int kk = 0; kk < 2; ++kk) {
;         bf16x8 pb[2];
; #pragma unroll
;         for (int qt = 0; qt < 2; ++qt) {
;           const float e0 = ex2(s[2 * kk][qt][0]), e1 = ex2(s[2 * kk][qt][1]), e2 = ex2(s[2 * kk][qt][2]), e3 = ex2(s[2 * kk][qt][3]);
;           const float e4 = ex2(s[2 * kk + 1][qt][0]), e5 = ex2(s[2 * kk + 1][qt][1]), e6 = ex2(s[2 * kk + 1][qt][2]), e7 = ex2(s[2 * kk + 1][qt][3]);
;           u32x4 cw = {pack2(e0, e1), pack2(e2, e3), pack2(e4, e5), pack2(e6, e7)};
;           pb[qt] = __builtin_bit_cast(bf16x8, cw);
;         }
;         lacc[0] = __builtin_amdgcn_mfma_f32_16x16x32_bf16(ones, pb[0], lacc[0], 0, 0, 0);
;         lacc[1] = __builtin_amdgcn_mfma_f32_16x16x32_bf16(ones, pb[1], lacc[1], 0, 0, 0);
; #pragma unroll
;         for (int dvf = 0; dvf < 4; ++dvf) {
;           const char* vp = vb + (dvf * 16 + fr) * VROW + (hh * 64 + kk * 32 + fq * 4) * 2;
;           const uint2 h0 = *(const uint2*)vp, h1 = *(const uint2*)(vp + 32);
;           u32x4 vw = {h0.x, h0.y, h1.x, h1.y};
;           const bf16x8 va = __builtin_bit_cast(bf16x8, vw);
;           o[dvf][0] = __builtin_amdgcn_mfma_f32_16x16x32_bf16(va, pb[0], o[dvf][0], 0, 0, 0);
;           o[dvf][1] = __builtin_amdgcn_mfma_f32_16x16x32_bf16(va, pb[1], o[dvf][1], 0, 0, 0);
;         }
;       }
;     }
;     if (t + 1 < nt) {
;       char* nb = smem + ((t + 1) & 1) * ASTG;
; #pragma unroll
;       for (int i = 0; i < 3; ++i) *(u32x4*)(nb + koff[i]) = kr[i];
; #pragma unroll
;       for (int i = 0; i < 2; ++i) *(u32x4*)(nb + KBYTES + voffl[i]) = vr[i];
;     }
;     __syncthreads();
	v_mfma_f32_16x16x32_bf16 v[32:35], v[214:217], v[144:147], v[32:35]
	v_exp_f32_e32 v112, v112
	v_exp_f32_e32 v113, v113
	v_mfma_f32_16x16x32_bf16 v[36:39], v[214:217], v[148:151], v[36:39]
	v_exp_f32_e32 v114, v114
	v_exp_f32_e32 v115, v115
	v_exp_f32_e32 v108, v108
	v_mfma_f32_16x16x32_bf16 v[40:43], v[218:221], v[144:147], v[40:43]
	v_exp_f32_e32 v109, v109
	v_exp_f32_e32 v110, v110
	v_mfma_f32_16x16x32_bf16 v[60:63], v[218:221], v[148:151], v[60:63]
	v_exp_f32_e32 v111, v111
	v_exp_f32_e32 v116, v116
	v_exp_f32_e32 v117, v117
	v_mfma_f32_16x16x32_bf16 v[44:47], v[222:225], v[144:147], v[44:47]
	v_exp_f32_e32 v118, v118
	v_exp_f32_e32 v119, v119
	v_mfma_f32_16x16x32_bf16 v[64:67], v[222:225], v[148:151], v[64:67]
	v_cvt_pk_bf16_f32 v136, v104, v105
	v_cvt_pk_bf16_f32 v137, v106, v107
	v_cvt_pk_bf16_f32 v138, v112, v113
	v_mfma_f32_16x16x32_bf16 v[48:51], v[226:229], v[144:147], v[48:51]
	v_cvt_pk_bf16_f32 v139, v114, v115
	v_cvt_pk_bf16_f32 v140, v108, v109
	v_mfma_f32_16x16x32_bf16 v[52:55], v[226:229], v[148:151], v[52:55]
	v_cvt_pk_bf16_f32 v141, v110, v111
	v_cvt_pk_bf16_f32 v142, v116, v117
	v_cvt_pk_bf16_f32 v143, v118, v119
	ds_read_b64 v[214:215], v180 offset:28864
	ds_read_b64 v[216:217], v180 offset:28896
	ds_read_b64 v[218:219], v180 offset:33216
	ds_read_b64 v[220:221], v180 offset:33248
	ds_read_b64 v[222:223], v180 offset:37568
	ds_read_b64 v[224:225], v180 offset:37600
	ds_read_b64 v[226:227], v180 offset:41920
	ds_read_b64 v[228:229], v180 offset:41952
	s_nop 1
	v_mfma_f32_16x16x32_bf16 v[68:71], v[152:155], v[136:139], v[68:71]
	v_exp_f32_e32 v120, v120
	v_exp_f32_e32 v121, v121
	v_mfma_f32_16x16x32_bf16 v[56:59], v[152:155], v[140:143], v[56:59]
	v_exp_f32_e32 v122, v122
	v_exp_f32_e32 v123, v123
	s_waitcnt lgkmcnt(8)
	v_mfma_f32_16x16x32_bf16 v[32:35], v[198:201], v[136:139], v[32:35]
	v_exp_f32_e32 v128, v128
	v_exp_f32_e32 v129, v129
	v_mfma_f32_16x16x32_bf16 v[36:39], v[198:201], v[140:143], v[36:39]
	v_exp_f32_e32 v130, v130
	v_exp_f32_e32 v131, v131
	v_exp_f32_e32 v124, v124
	v_mfma_f32_16x16x32_bf16 v[40:43], v[202:205], v[136:139], v[40:43]
	v_exp_f32_e32 v125, v125
	v_exp_f32_e32 v126, v126
	v_mfma_f32_16x16x32_bf16 v[60:63], v[202:205], v[140:143], v[60:63]
	v_exp_f32_e32 v127, v127
	v_exp_f32_e32 v132, v132
	v_exp_f32_e32 v133, v133
	v_mfma_f32_16x16x32_bf16 v[44:47], v[206:209], v[136:139], v[44:47]
	v_exp_f32_e32 v134, v134
	v_exp_f32_e32 v135, v135
	v_mfma_f32_16x16x32_bf16 v[64:67], v[206:209], v[140:143], v[64:67]
	v_cvt_pk_bf16_f32 v144, v120, v121
	v_cvt_pk_bf16_f32 v145, v122, v123
	v_cvt_pk_bf16_f32 v146, v128, v129
	v_mfma_f32_16x16x32_bf16 v[48:51], v[210:213], v[136:139], v[48:51]
	v_cvt_pk_bf16_f32 v147, v130, v131
	v_cvt_pk_bf16_f32 v148, v124, v125
	v_mfma_f32_16x16x32_bf16 v[52:55], v[210:213], v[140:143], v[52:55]
	v_cvt_pk_bf16_f32 v149, v126, v127
	v_cvt_pk_bf16_f32 v150, v132, v133
	v_cvt_pk_bf16_f32 v151, v134, v135
	s_nop 1
	v_mfma_f32_16x16x32_bf16 v[68:71], v[152:155], v[144:147], v[68:71]
	v_mfma_f32_16x16x32_bf16 v[56:59], v[152:155], v[148:151], v[56:59]
	s_waitcnt lgkmcnt(0)
	v_mfma_f32_16x16x32_bf16 v[32:35], v[214:217], v[144:147], v[32:35]
	v_mfma_f32_16x16x32_bf16 v[36:39], v[214:217], v[148:151], v[36:39]
	v_mfma_f32_16x16x32_bf16 v[40:43], v[218:221], v[144:147], v[40:43]
	v_mfma_f32_16x16x32_bf16 v[60:63], v[218:221], v[148:151], v[60:63]
	v_mfma_f32_16x16x32_bf16 v[44:47], v[222:225], v[144:147], v[44:47]
	v_mfma_f32_16x16x32_bf16 v[64:67], v[222:225], v[148:151], v[64:67]
	v_mfma_f32_16x16x32_bf16 v[48:51], v[226:229], v[144:147], v[48:51]
	v_mfma_f32_16x16x32_bf16 v[52:55], v[226:229], v[148:151], v[52:55]
	s_waitcnt lgkmcnt(0)
	s_barrier
	s_mov_b32 s18, s15
	s_mov_b32 s15, s12
	s_mov_b32 s12, s9
	s_mov_b32 s9, s18
	s_add_i32 s13, s13, 1
	s_cmp_lg_u32 s13, 16
	s_cbranch_scc1 .Lattn_a_loop
	global_load_dwordx4 v[230:233], v[164:165], off
	global_load_dwordx4 v[234:237], v[166:167], off
	global_load_dwordx4 v[238:241], v[168:169], off
	global_load_dwordx4 v[242:245], v[170:171], off
	global_load_dwordx4 v[246:249], v[172:173], off
	v_lshl_add_u64 v[164:165], v[164:165], 0, s[26:27]
	v_lshl_add_u64 v[166:167], v[166:167], 0, s[26:27]
	v_lshl_add_u64 v[168:169], v[168:169], 0, s[16:17]
	v_lshl_add_u64 v[170:171], v[170:171], 0, s[16:17]
	v_lshl_add_u64 v[172:173], v[172:173], 0, s[16:17]
	v_add_u32_e32 v184, s9, v159
	v_add_u32_e32 v185, s9, v161
	v_add_u32_e32 v186, s9, v163
	v_add_u32_e32 v187, s9, v160
	v_add_u32_e32 v188, s9, v162
	v_add3_u32 v179, s12, v156, v181
	ds_read_b128 v[198:201], v179
	ds_read_b128 v[202:205], v179 offset:3584
	ds_read_b128 v[206:209], v179 offset:7168
	ds_read_b128 v[210:213], v179 offset:10752
	ds_read_b128 v[214:217], v179 offset:64
	ds_read_b128 v[218:221], v179 offset:3648
	ds_read_b128 v[222:225], v179 offset:7232
	ds_read_b128 v[226:229], v179 offset:10816
	s_waitcnt lgkmcnt(7)
	v_mfma_f32_16x16x32_bf16 v[72:75], v[198:201], v[12:15], v[24:27]
	v_mfma_f32_16x16x32_bf16 v[76:79], v[198:201], v[20:23], v[28:31]
	ds_read_b128 v[198:201], v179 offset:128
	s_waitcnt lgkmcnt(7)
	v_mfma_f32_16x16x32_bf16 v[80:83], v[202:205], v[12:15], v[24:27]
	v_mfma_f32_16x16x32_bf16 v[84:87], v[202:205], v[20:23], v[28:31]
	ds_read_b128 v[202:205], v179 offset:3712
	s_waitcnt lgkmcnt(7)
	v_mfma_f32_16x16x32_bf16 v[88:91], v[206:209], v[12:15], v[24:27]
	v_mfma_f32_16x16x32_bf16 v[92:95], v[206:209], v[20:23], v[28:31]
	ds_read_b128 v[206:209], v179 offset:7296
	s_waitcnt lgkmcnt(7)
	v_mfma_f32_16x16x32_bf16 v[96:99], v[210:213], v[12:15], v[24:27]
	v_mfma_f32_16x16x32_bf16 v[100:103], v[210:213], v[20:23], v[28:31]
	ds_read_b128 v[210:213], v179 offset:10880
	s_waitcnt lgkmcnt(7)
; DEV float ex2(float x) { return __builtin_amdgcn_exp2f(x); }
; DEV void attn_item(const Params& p, int bl, int head, int q0, int nkeys, char* smem, int tid) {
;     ...
;     for (int hh = 0; hh < 2; ++hh) {
;       f32x4 s[4][2];
; #pragma unroll
;       for (int kf = 0; kf < 4; ++kf) {
; #pragma unroll
;         for (int ks = 0; ks < 3; ++ks) {
;           bf16x8 a = *(const bf16x8*)(kb + (hh * 64 + kf * 16 + fr) * KROW + ks * 64 + fq * 16);
;           s[kf][0] = __builtin_amdgcn_mfma_f32_16x16x32_bf16(a, qf[0][ks], ks == 0 ? negm[0] : s[kf][0], 0, 0, 0);
;           s[kf][1] = __builtin_amdgcn_mfma_f32_16x16x32_bf16(a, qf[1][ks], ks == 0 ? negm[1] : s[kf][1], 0, 0, 0);
;         }
;       }
; #pragma unroll
;       for (int kk = 0; kk < 2; ++kk) {
;         bf16x8 pb[2];
; #pragma unroll
;         for (int qt = 0; qt < 2; ++qt) {
;           const float e0 = ex2(s[2 * kk][qt][0]), e1 = ex2(s[2 * kk][qt][1]), e2 = ex2(s[2 * kk][qt][2]), e3 = ex2(s[2 * kk][qt][3]);
;           const float e4 = ex2(s[2 * kk + 1][qt][0]), e5 = ex2(s[2 * kk + 1][qt][1]), e6 = ex2(s[2 * kk + 1][qt][2]), e7 = ex2(s[2 * kk + 1][qt][3]);
;           u32x4 cw = {pack2(e0, e1), pack2(e2, e3), pack2(e4, e5), pack2(e6, e7)};
;           pb[qt] = __builtin_bit_cast(bf16x8, cw);
;         }
;         lacc[0] = __builtin_amdgcn_mfma_f32_16x16x32_bf16(ones, pb[0], lacc[0], 0, 0, 0);
;         lacc[1] = __builtin_amdgcn_mfma_f32_16x16x32_bf16(ones, pb[1], lacc[1], 0, 0, 0);
; #pragma unroll
;         for (int dvf = 0; dvf < 4; ++dvf) {
;           const char* vp = vb + (dvf * 16 + fr) * VROW + (hh * 64 + kk * 32 + fq * 4) * 2;
;           const uint2 h0 = *(const uint2*)vp, h1 = *(const uint2*)(vp + 32);
;           u32x4 vw = {h0.x, h0.y, h1.x, h1.y};
;           const bf16x8 va = __builtin_bit_cast(bf16x8, vw);
;           o[dvf][0] = __builtin_amdgcn_mfma_f32_16x16x32_bf16(va, pb[0], o[dvf][0], 0, 0, 0);
;           o[dvf][1] = __builtin_amdgcn_mfma_f32_16x16x32_bf16(va, pb[1], o[dvf][1], 0, 0, 0);
;         }
	v_mfma_f32_16x16x32_bf16 v[72:75], v[214:217], v[8:11], v[72:75]
	v_mfma_f32_16x16x32_bf16 v[76:79], v[214:217], v[16:19], v[76:79]
	ds_read_b128 v[214:217], v179 offset:14336
	s_waitcnt lgkmcnt(7)
	v_mfma_f32_16x16x32_bf16 v[80:83], v[218:221], v[8:11], v[80:83]
	v_mfma_f32_16x16x32_bf16 v[84:87], v[218:221], v[16:19], v[84:87]
	ds_read_b128 v[218:221], v179 offset:17920
	s_waitcnt lgkmcnt(7)
	v_mfma_f32_16x16x32_bf16 v[88:91], v[222:225], v[8:11], v[88:91]
	v_mfma_f32_16x16x32_bf16 v[92:95], v[222:225], v[16:19], v[92:95]
	ds_read_b128 v[222:225], v179 offset:21504
	s_waitcnt lgkmcnt(7)
	v_mfma_f32_16x16x32_bf16 v[96:99], v[226:229], v[8:11], v[96:99]
	v_mfma_f32_16x16x32_bf16 v[100:103], v[226:229], v[16:19], v[100:103]
	ds_read_b128 v[226:229], v179 offset:25088
	s_waitcnt lgkmcnt(7)
	v_mfma_f32_16x16x32_bf16 v[72:75], v[198:201], v[4:7], v[72:75]
	v_mfma_f32_16x16x32_bf16 v[76:79], v[198:201], v[0:3], v[76:79]
	ds_read_b128 v[198:201], v179 offset:14400
	s_waitcnt lgkmcnt(7)
	v_mfma_f32_16x16x32_bf16 v[80:83], v[202:205], v[4:7], v[80:83]
	v_mfma_f32_16x16x32_bf16 v[84:87], v[202:205], v[0:3], v[84:87]
	ds_read_b128 v[202:205], v179 offset:17984
	s_waitcnt lgkmcnt(7)
	v_mfma_f32_16x16x32_bf16 v[88:91], v[206:209], v[4:7], v[88:91]
	v_mfma_f32_16x16x32_bf16 v[92:95], v[206:209], v[0:3], v[92:95]
	ds_read_b128 v[206:209], v179 offset:21568
	s_waitcnt lgkmcnt(7)
	v_mfma_f32_16x16x32_bf16 v[96:99], v[210:213], v[4:7], v[96:99]
	v_mfma_f32_16x16x32_bf16 v[100:103], v[210:213], v[0:3], v[100:103]
	ds_read_b128 v[210:213], v179 offset:25152
	s_waitcnt lgkmcnt(7)
	v_mfma_f32_16x16x32_bf16 v[104:107], v[214:217], v[12:15], v[24:27]
	v_mfma_f32_16x16x32_bf16 v[108:111], v[214:217], v[20:23], v[28:31]
	ds_read_b128 v[214:217], v179 offset:14464
	s_waitcnt lgkmcnt(7)
	v_mfma_f32_16x16x32_bf16 v[112:115], v[218:221], v[12:15], v[24:27]
	v_mfma_f32_16x16x32_bf16 v[116:119], v[218:221], v[20:23], v[28:31]
	ds_read_b128 v[218:221], v179 offset:18048
	s_waitcnt lgkmcnt(7)
	v_mfma_f32_16x16x32_bf16 v[120:123], v[222:225], v[12:15], v[24:27]
	v_exp_f32_e32 v72, v72
	v_mfma_f32_16x16x32_bf16 v[124:127], v[222:225], v[20:23], v[28:31]
	v_exp_f32_e32 v73, v73
	ds_read_b128 v[222:225], v179 offset:21632
	s_waitcnt lgkmcnt(7)
	v_mfma_f32_16x16x32_bf16 v[128:131], v[226:229], v[12:15], v[24:27]
	v_exp_f32_e32 v74, v74
	v_mfma_f32_16x16x32_bf16 v[132:135], v[226:229], v[20:23], v[28:31]
	v_exp_f32_e32 v75, v75
	ds_read_b128 v[226:229], v179 offset:25216
	s_waitcnt lgkmcnt(7)
	v_mfma_f32_16x16x32_bf16 v[104:107], v[198:201], v[8:11], v[104:107]
	v_exp_f32_e32 v80, v80
	v_exp_f32_e32 v81, v81
	v_mfma_f32_16x16x32_bf16 v[108:111], v[198:201], v[16:19], v[108:111]
	v_exp_f32_e32 v82, v82
	s_waitcnt lgkmcnt(6)
	v_mfma_f32_16x16x32_bf16 v[112:115], v[202:205], v[8:11], v[112:115]
	v_exp_f32_e32 v83, v83
	v_mfma_f32_16x16x32_bf16 v[116:119], v[202:205], v[16:19], v[116:119]
	v_exp_f32_e32 v76, v76
	s_waitcnt lgkmcnt(5)
	v_mfma_f32_16x16x32_bf16 v[120:123], v[206:209], v[8:11], v[120:123]
	v_exp_f32_e32 v77, v77
	v_mfma_f32_16x16x32_bf16 v[124:127], v[206:209], v[16:19], v[124:127]
	v_exp_f32_e32 v78, v78
	v_exp_f32_e32 v79, v79
	s_waitcnt lgkmcnt(4)
	v_mfma_f32_16x16x32_bf16 v[128:131], v[210:213], v[8:11], v[128:131]
	v_exp_f32_e32 v84, v84
	v_mfma_f32_16x16x32_bf16 v[132:135], v[210:213], v[16:19], v[132:135]
	v_exp_f32_e32 v85, v85
	s_waitcnt lgkmcnt(3)
	v_mfma_f32_16x16x32_bf16 v[104:107], v[214:217], v[4:7], v[104:107]
	v_exp_f32_e32 v86, v86
	v_mfma_f32_16x16x32_bf16 v[108:111], v[214:217], v[0:3], v[108:111]
	v_exp_f32_e32 v87, v87
	s_waitcnt lgkmcnt(2)
	v_mfma_f32_16x16x32_bf16 v[112:115], v[218:221], v[4:7], v[112:115]
	v_cvt_pk_bf16_f32 v136, v72, v73
	v_cvt_pk_bf16_f32 v137, v74, v75
	v_mfma_f32_16x16x32_bf16 v[116:119], v[218:221], v[0:3], v[116:119]
	v_cvt_pk_bf16_f32 v138, v80, v81
	s_waitcnt lgkmcnt(1)
	v_mfma_f32_16x16x32_bf16 v[120:123], v[222:225], v[4:7], v[120:123]
	v_cvt_pk_bf16_f32 v139, v82, v83
	v_mfma_f32_16x16x32_bf16 v[124:127], v[222:225], v[0:3], v[124:127]
	v_cvt_pk_bf16_f32 v140, v76, v77
	s_waitcnt lgkmcnt(0)
	v_mfma_f32_16x16x32_bf16 v[128:131], v[226:229], v[4:7], v[128:131]
	v_cvt_pk_bf16_f32 v141, v78, v79
	v_mfma_f32_16x16x32_bf16 v[132:135], v[226:229], v[0:3], v[132:135]
	v_cvt_pk_bf16_f32 v142, v84, v85
	v_cvt_pk_bf16_f32 v143, v86, v87
	s_waitcnt vmcnt(0)
	ds_write_b128 v184, v[238:241]
	ds_write_b128 v185, v[242:245]
	ds_write_b128 v186, v[246:249]
	ds_write_b128 v187, v[230:233] offset:26624
	ds_write_b128 v188, v[234:237] offset:26624
	v_add3_u32 v180, s12, v176, v177
	ds_read_b64 v[198:199], v180 offset:28672
	ds_read_b64 v[200:201], v180 offset:28704
	ds_read_b64 v[202:203], v180 offset:33024
	ds_read_b64 v[204:205], v180 offset:33056
	ds_read_b64 v[206:207], v180 offset:37376
	ds_read_b64 v[208:209], v180 offset:37408
	ds_read_b64 v[210:211], v180 offset:41728
	ds_read_b64 v[212:213], v180 offset:41760
	ds_read_b64 v[214:215], v180 offset:28736
	ds_read_b64 v[216:217], v180 offset:28768
	ds_read_b64 v[218:219], v180 offset:33088
	ds_read_b64 v[220:221], v180 offset:33120
	ds_read_b64 v[222:223], v180 offset:37440
	ds_read_b64 v[224:225], v180 offset:37472
	ds_read_b64 v[226:227], v180 offset:41792
	ds_read_b64 v[228:229], v180 offset:41824
	v_mfma_f32_16x16x32_bf16 v[68:71], v[152:155], v[136:139], v[68:71]
	v_exp_f32_e32 v88, v88
	v_exp_f32_e32 v89, v89
	v_mfma_f32_16x16x32_bf16 v[56:59], v[152:155], v[140:143], v[56:59]
	v_exp_f32_e32 v90, v90
	v_exp_f32_e32 v91, v91
	s_waitcnt lgkmcnt(8)
; DEV float ex2(float x) { return __builtin_amdgcn_exp2f(x); }
; DEV void attn_item(const Params& p, int bl, int head, int q0, int nkeys, char* smem, int tid) {
;     ...
; #pragma unroll
;       for (int kk = 0; kk < 2; ++kk) {
;         bf16x8 pb[2];
; #pragma unroll
;         for (int qt = 0; qt < 2; ++qt) {
;           const float e0 = ex2(s[2 * kk][qt][0]), e1 = ex2(s[2 * kk][qt][1]), e2 = ex2(s[2 * kk][qt][2]), e3 = ex2(s[2 * kk][qt][3]);
;           const float e4 = ex2(s[2 * kk + 1][qt][0]), e5 = ex2(s[2 * kk + 1][qt][1]), e6 = ex2(s[2 * kk + 1][qt][2]), e7 = ex2(s[2 * kk + 1][qt][3]);
;           u32x4 cw = {pack2(e0, e1), pack2(e2, e3), pack2(e4, e5), pack2(e6, e7)};
;           pb[qt] = __builtin_bit_cast(bf16x8, cw);
;         }
;         lacc[0] = __builtin_amdgcn_mfma_f32_16x16x32_bf16(ones, pb[0], lacc[0], 0, 0, 0);
;         lacc[1] = __builtin_amdgcn_mfma_f32_16x16x32_bf16(ones, pb[1], lacc[1], 0, 0, 0);
; #pragma unroll
;         for (int dvf = 0; dvf < 4; ++dvf) {
;           const char* vp = vb + (dvf * 16 + fr) * VROW + (hh * 64 + kk * 32 + fq * 4) * 2;
;           const uint2 h0 = *(const uint2*)vp, h1 = *(const uint2*)(vp + 32);
;           u32x4 vw = {h0.x, h0.y, h1.x, h1.y};
;           const bf16x8 va = __builtin_bit_cast(bf16x8, vw);
;           o[dvf][0] = __builtin_amdgcn_mfma_f32_16x16x32_bf16(va, pb[0], o[dvf][0], 0, 0, 0);
;           o[dvf][1] = __builtin_amdgcn_mfma_f32_16x16x32_bf16(va, pb[1], o[dvf][1], 0, 0, 0);
;         }
;       }
;     }
;     if (t + 1 < nt) {
;       char* nb = smem + ((t + 1) & 1) * ASTG;
; #pragma unroll
;       for (int i = 0; i < 3; ++i) *(u32x4*)(nb + koff[i]) = kr[i];
; #pragma unroll
;       for (int i = 0; i < 2; ++i) *(u32x4*)(nb + KBYTES + voffl[i]) = vr[i];
;     }
;     __syncthreads();
	v_mfma_f32_16x16x32_bf16 v[32:35], v[198:201], v[136:139], v[32:35]
	v_exp_f32_e32 v96, v96
	v_exp_f32_e32 v97, v97
	v_mfma_f32_16x16x32_bf16 v[36:39], v[198:201], v[140:143], v[36:39]
	v_exp_f32_e32 v98, v98
	v_exp_f32_e32 v99, v99
	v_exp_f32_e32 v92, v92
	v_mfma_f32_16x16x32_bf16 v[40:43], v[202:205], v[136:139], v[40:43]
	v_exp_f32_e32 v93, v93
	v_exp_f32_e32 v94, v94
	v_mfma_f32_16x16x32_bf16 v[60:63], v[202:205], v[140:143], v[60:63]
	v_exp_f32_e32 v95, v95
	v_exp_f32_e32 v100, v100
	v_exp_f32_e32 v101, v101
	v_mfma_f32_16x16x32_bf16 v[44:47], v[206:209], v[136:139], v[44:47]
	v_exp_f32_e32 v102, v102
	v_exp_f32_e32 v103, v103
	v_mfma_f32_16x16x32_bf16 v[64:67], v[206:209], v[140:143], v[64:67]
	v_cvt_pk_bf16_f32 v144, v88, v89
	v_cvt_pk_bf16_f32 v145, v90, v91
	v_cvt_pk_bf16_f32 v146, v96, v97
	v_mfma_f32_16x16x32_bf16 v[48:51], v[210:213], v[136:139], v[48:51]
	v_cvt_pk_bf16_f32 v147, v98, v99
	v_cvt_pk_bf16_f32 v148, v92, v93
	v_mfma_f32_16x16x32_bf16 v[52:55], v[210:213], v[140:143], v[52:55]
	v_cvt_pk_bf16_f32 v149, v94, v95
	v_cvt_pk_bf16_f32 v150, v100, v101
	v_cvt_pk_bf16_f32 v151, v102, v103
	ds_read_b64 v[198:199], v180 offset:28800
	ds_read_b64 v[200:201], v180 offset:28832
	ds_read_b64 v[202:203], v180 offset:33152
	ds_read_b64 v[204:205], v180 offset:33184
	ds_read_b64 v[206:207], v180 offset:37504
	ds_read_b64 v[208:209], v180 offset:37536
	ds_read_b64 v[210:211], v180 offset:41856
	ds_read_b64 v[212:213], v180 offset:41888
	s_nop 1
	v_mfma_f32_16x16x32_bf16 v[68:71], v[152:155], v[144:147], v[68:71]
	v_exp_f32_e32 v104, v104
	v_exp_f32_e32 v105, v105
	v_mfma_f32_16x16x32_bf16 v[56:59], v[152:155], v[148:151], v[56:59]
	v_exp_f32_e32 v106, v106
	v_exp_f32_e32 v107, v107
	s_waitcnt lgkmcnt(8)
	v_mfma_f32_16x16x32_bf16 v[32:35], v[214:217], v[144:147], v[32:35]
	v_exp_f32_e32 v112, v112
	v_exp_f32_e32 v113, v113
	v_mfma_f32_16x16x32_bf16 v[36:39], v[214:217], v[148:151], v[36:39]
	v_exp_f32_e32 v114, v114
	v_exp_f32_e32 v115, v115
	v_exp_f32_e32 v108, v108
	v_mfma_f32_16x16x32_bf16 v[40:43], v[218:221], v[144:147], v[40:43]
	v_exp_f32_e32 v109, v109
	v_exp_f32_e32 v110, v110
	v_mfma_f32_16x16x32_bf16 v[60:63], v[218:221], v[148:151], v[60:63]
	v_exp_f32_e32 v111, v111
	v_exp_f32_e32 v116, v116
	v_exp_f32_e32 v117, v117
	v_mfma_f32_16x16x32_bf16 v[44:47], v[222:225], v[144:147], v[44:47]
	v_exp_f32_e32 v118, v118
	v_exp_f32_e32 v119, v119
	v_mfma_f32_16x16x32_bf16 v[64:67], v[222:225], v[148:151], v[64:67]
	v_cvt_pk_bf16_f32 v136, v104, v105
	v_cvt_pk_bf16_f32 v137, v106, v107
	v_cvt_pk_bf16_f32 v138, v112, v113
	v_mfma_f32_16x16x32_bf16 v[48:51], v[226:229], v[144:147], v[48:51]
	v_cvt_pk_bf16_f32 v139, v114, v115
	v_cvt_pk_bf16_f32 v140, v108, v109
	v_mfma_f32_16x16x32_bf16 v[52:55], v[226:229], v[148:151], v[52:55]
	v_cvt_pk_bf16_f32 v141, v110, v111
	v_cvt_pk_bf16_f32 v142, v116, v117
	v_cvt_pk_bf16_f32 v143, v118, v119
	ds_read_b64 v[214:215], v180 offset:28864
	ds_read_b64 v[216:217], v180 offset:28896
	ds_read_b64 v[218:219], v180 offset:33216
	ds_read_b64 v[220:221], v180 offset:33248
	ds_read_b64 v[222:223], v180 offset:37568
	ds_read_b64 v[224:225], v180 offset:37600
	ds_read_b64 v[226:227], v180 offset:41920
	ds_read_b64 v[228:229], v180 offset:41952
	s_nop 1
	v_mfma_f32_16x16x32_bf16 v[68:71], v[152:155], v[136:139], v[68:71]
	v_exp_f32_e32 v120, v120
	v_exp_f32_e32 v121, v121
	v_mfma_f32_16x16x32_bf16 v[56:59], v[152:155], v[140:143], v[56:59]
	v_exp_f32_e32 v122, v122
	v_exp_f32_e32 v123, v123
	s_waitcnt lgkmcnt(8)
	v_mfma_f32_16x16x32_bf16 v[32:35], v[198:201], v[136:139], v[32:35]
	v_exp_f32_e32 v128, v128
	v_exp_f32_e32 v129, v129
	v_mfma_f32_16x16x32_bf16 v[36:39], v[198:201], v[140:143], v[36:39]
	v_exp_f32_e32 v130, v130
	v_exp_f32_e32 v131, v131
	v_exp_f32_e32 v124, v124
	v_mfma_f32_16x16x32_bf16 v[40:43], v[202:205], v[136:139], v[40:43]
	v_exp_f32_e32 v125, v125
	v_exp_f32_e32 v126, v126
	v_mfma_f32_16x16x32_bf16 v[60:63], v[202:205], v[140:143], v[60:63]
	v_exp_f32_e32 v127, v127
	v_exp_f32_e32 v132, v132
	v_exp_f32_e32 v133, v133
	v_mfma_f32_16x16x32_bf16 v[44:47], v[206:209], v[136:139], v[44:47]
	v_exp_f32_e32 v134, v134
	v_exp_f32_e32 v135, v135
	v_mfma_f32_16x16x32_bf16 v[64:67], v[206:209], v[140:143], v[64:67]
	v_cvt_pk_bf16_f32 v144, v120, v121
	v_cvt_pk_bf16_f32 v145, v122, v123
	v_cvt_pk_bf16_f32 v146, v128, v129
	v_mfma_f32_16x16x32_bf16 v[48:51], v[210:213], v[136:139], v[48:51]
	v_cvt_pk_bf16_f32 v147, v130, v131
	v_cvt_pk_bf16_f32 v148, v124, v125
	v_mfma_f32_16x16x32_bf16 v[52:55], v[210:213], v[140:143], v[52:55]
	v_cvt_pk_bf16_f32 v149, v126, v127
	v_cvt_pk_bf16_f32 v150, v132, v133
	v_cvt_pk_bf16_f32 v151, v134, v135
	s_nop 1
	v_mfma_f32_16x16x32_bf16 v[68:71], v[152:155], v[144:147], v[68:71]
	v_mfma_f32_16x16x32_bf16 v[56:59], v[152:155], v[148:151], v[56:59]
	s_waitcnt lgkmcnt(0)
	v_mfma_f32_16x16x32_bf16 v[32:35], v[214:217], v[144:147], v[32:35]
	v_mfma_f32_16x16x32_bf16 v[36:39], v[214:217], v[148:151], v[36:39]
	v_mfma_f32_16x16x32_bf16 v[40:43], v[218:221], v[144:147], v[40:43]
	v_mfma_f32_16x16x32_bf16 v[60:63], v[218:221], v[148:151], v[60:63]
	v_mfma_f32_16x16x32_bf16 v[44:47], v[222:225], v[144:147], v[44:47]
	v_mfma_f32_16x16x32_bf16 v[64:67], v[222:225], v[148:151], v[64:67]
	v_mfma_f32_16x16x32_bf16 v[48:51], v[226:229], v[144:147], v[48:51]
	v_mfma_f32_16x16x32_bf16 v[52:55], v[226:229], v[148:151], v[52:55]
	s_waitcnt lgkmcnt(0)
	s_barrier
	s_mov_b32 s18, s15
	s_mov_b32 s15, s12
	s_mov_b32 s12, s9
	s_mov_b32 s9, s18
	s_add_i32 s13, s13, 1
	s_branch .Lattn_tail
; DEV float ex2(float x) { return __builtin_amdgcn_exp2f(x); }
; DEV void attn_item(const Params& p, int bl, int head, int q0, int nkeys, char* smem, int tid) {
;     ...
;     if (t + 1 < nt) {
; #pragma unroll
;       for (int i = 0; i < 3; ++i) kr[i] = *(const u32x4*)(Kg + (long)(t + 1) * 128 * 96 + (long)(i * 512 + tid) * 8);
; #pragma unroll
;       for (int i = 0; i < 2; ++i) vr[i] = *(const u32x4*)(Vg + (t + 1) * 128 + voffg[i]);
;     }
;     const char* kb = smem + (t & 1) * ASTG;
;     const char* vb = kb + KBYTES;
; #pragma unroll
;     for (int hh = 0; hh < 2; ++hh) {
;       f32x4 s[4][2];
; #pragma unroll
;       for (int kf = 0; kf < 4; ++kf) {
; #pragma unroll
;         for (int ks = 0; ks < 3; ++ks) {
;           bf16x8 a = *(const bf16x8*)(kb + (hh * 64 + kf * 16 + fr) * KROW + ks * 64 + fq * 16);
;           s[kf][0] = __builtin_amdgcn_mfma_f32_16x16x32_bf16(a, qf[0][ks], ks == 0 ? negm[0] : s[kf][0], 0, 0, 0);
;           s[kf][1] = __builtin_amdgcn_mfma_f32_16x16x32_bf16(a, qf[1][ks], ks == 0 ? negm[1] : s[kf][1], 0, 0, 0);
;         }
;       }
; #pragma unroll
;       for (int kk = 0; kk < 2; ++kk) {
;         bf16x8 pb[2];
; #pragma unroll
;         for (int qt = 0; qt < 2; ++qt) {
;           const float e0 = ex2(s[2 * kk][qt][0]), e1 = ex2(s[2 * kk][qt][1]), e2 = ex2(s[2 * kk][qt][2]), e3 = ex2(s[2 * kk][qt][3]);
;           const float e4 = ex2(s[2 * kk + 1][qt][0]), e5 = ex2(s[2 * kk + 1][qt][1]), e6 = ex2(s[2 * kk + 1][qt][2]), e7 = ex2(s[2 * kk + 1][qt][3]);
;           u32x4 cw = {pack2(e0, e1), pack2(e2, e3), pack2(e4, e5), pack2(e6, e7)};
;           pb[qt] = __builtin_bit_cast(bf16x8, cw);
;         }
.Lattn_b_pre:
	global_load_dwordx4 v[230:233], v[164:165], off
	global_load_dwordx4 v[234:237], v[166:167], off
	global_load_dwordx4 v[238:241], v[168:169], off
	global_load_dwordx4 v[242:245], v[170:171], off
	global_load_dwordx4 v[246:249], v[172:173], off
	v_lshl_add_u64 v[164:165], v[164:165], 0, s[26:27]
	v_lshl_add_u64 v[166:167], v[166:167], 0, s[26:27]
	v_lshl_add_u64 v[168:169], v[168:169], 0, s[16:17]
	v_lshl_add_u64 v[170:171], v[170:171], 0, s[16:17]
	v_lshl_add_u64 v[172:173], v[172:173], 0, s[16:17]
	v_add_u32_e32 v184, s9, v190
	v_add_u32_e32 v185, s9, v191
	v_add_u32_e32 v186, s9, v192
	v_add_u32_e32 v187, s9, v160
	v_add_u32_e32 v188, s9, v162
	s_waitcnt vmcnt(0)
	ds_write_b128 v184, v[238:241]
	ds_write_b128 v185, v[242:245]
	ds_write_b128 v186, v[246:249]
	ds_write_b128 v187, v[230:233] offset:28672
	ds_write_b128 v188, v[234:237] offset:28672
	v_add3_u32 v179, s12, v156, v178
	ds_read_b128 v[198:201], v179
	ds_read_b128 v[202:205], v179 offset:3328
	ds_read_b128 v[206:209], v179 offset:6656
	ds_read_b128 v[210:213], v179 offset:9984
	ds_read_b128 v[214:217], v179 offset:64
	ds_read_b128 v[218:221], v179 offset:3392
	ds_read_b128 v[222:225], v179 offset:6720
	ds_read_b128 v[226:229], v179 offset:10048
	s_waitcnt lgkmcnt(7)
	v_mfma_f32_16x16x32_bf16 v[72:75], v[198:201], v[12:15], v[24:27]
	v_mfma_f32_16x16x32_bf16 v[76:79], v[198:201], v[20:23], v[28:31]
	ds_read_b128 v[198:201], v179 offset:128
	s_waitcnt lgkmcnt(7)
	v_mfma_f32_16x16x32_bf16 v[80:83], v[202:205], v[12:15], v[24:27]
	v_mfma_f32_16x16x32_bf16 v[84:87], v[202:205], v[20:23], v[28:31]
	ds_read_b128 v[202:205], v179 offset:3456
	s_waitcnt lgkmcnt(7)
	v_mfma_f32_16x16x32_bf16 v[88:91], v[206:209], v[12:15], v[24:27]
	v_mfma_f32_16x16x32_bf16 v[92:95], v[206:209], v[20:23], v[28:31]
	ds_read_b128 v[206:209], v179 offset:6784
	s_waitcnt lgkmcnt(7)
	v_mfma_f32_16x16x32_bf16 v[96:99], v[210:213], v[12:15], v[24:27]
	v_mfma_f32_16x16x32_bf16 v[100:103], v[210:213], v[20:23], v[28:31]
	ds_read_b128 v[210:213], v179 offset:10112
	s_waitcnt lgkmcnt(7)
	v_mfma_f32_16x16x32_bf16 v[72:75], v[214:217], v[8:11], v[72:75]
	v_mfma_f32_16x16x32_bf16 v[76:79], v[214:217], v[16:19], v[76:79]
	ds_read_b128 v[214:217], v179 offset:13312
	s_waitcnt lgkmcnt(7)
	v_mfma_f32_16x16x32_bf16 v[80:83], v[218:221], v[8:11], v[80:83]
	v_mfma_f32_16x16x32_bf16 v[84:87], v[218:221], v[16:19], v[84:87]
	ds_read_b128 v[218:221], v179 offset:16640
	s_waitcnt lgkmcnt(7)
	v_mfma_f32_16x16x32_bf16 v[88:91], v[222:225], v[8:11], v[88:91]
	v_mfma_f32_16x16x32_bf16 v[92:95], v[222:225], v[16:19], v[92:95]
	ds_read_b128 v[222:225], v179 offset:19968
	s_waitcnt lgkmcnt(7)
	v_mfma_f32_16x16x32_bf16 v[96:99], v[226:229], v[8:11], v[96:99]
	v_mfma_f32_16x16x32_bf16 v[100:103], v[226:229], v[16:19], v[100:103]
	ds_read_b128 v[226:229], v179 offset:23296
	s_waitcnt lgkmcnt(7)
	v_mfma_f32_16x16x32_bf16 v[72:75], v[198:201], v[4:7], v[72:75]
	v_mfma_f32_16x16x32_bf16 v[76:79], v[198:201], v[0:3], v[76:79]
	ds_read_b128 v[198:201], v179 offset:13376
	s_waitcnt lgkmcnt(7)
	v_mfma_f32_16x16x32_bf16 v[80:83], v[202:205], v[4:7], v[80:83]
	v_mfma_f32_16x16x32_bf16 v[84:87], v[202:205], v[0:3], v[84:87]
	ds_read_b128 v[202:205], v179 offset:16704
	s_waitcnt lgkmcnt(7)
	v_mfma_f32_16x16x32_bf16 v[88:91], v[206:209], v[4:7], v[88:91]
	v_mfma_f32_16x16x32_bf16 v[92:95], v[206:209], v[0:3], v[92:95]
	ds_read_b128 v[206:209], v179 offset:20032
	s_waitcnt lgkmcnt(7)
	v_mfma_f32_16x16x32_bf16 v[96:99], v[210:213], v[4:7], v[96:99]
	v_mfma_f32_16x16x32_bf16 v[100:103], v[210:213], v[0:3], v[100:103]
	ds_read_b128 v[210:213], v179 offset:23360
	s_waitcnt lgkmcnt(7)
	v_mfma_f32_16x16x32_bf16 v[104:107], v[214:217], v[12:15], v[24:27]
	v_mfma_f32_16x16x32_bf16 v[108:111], v[214:217], v[20:23], v[28:31]
	ds_read_b128 v[214:217], v179 offset:13440
	s_waitcnt lgkmcnt(7)
	v_mfma_f32_16x16x32_bf16 v[112:115], v[218:221], v[12:15], v[24:27]
	v_mfma_f32_16x16x32_bf16 v[116:119], v[218:221], v[20:23], v[28:31]
	ds_read_b128 v[218:221], v179 offset:16768
	s_waitcnt lgkmcnt(7)
	v_mfma_f32_16x16x32_bf16 v[120:123], v[222:225], v[12:15], v[24:27]
	v_exp_f32_e32 v72, v72
	v_mfma_f32_16x16x32_bf16 v[124:127], v[222:225], v[20:23], v[28:31]
	v_exp_f32_e32 v73, v73
	ds_read_b128 v[222:225], v179 offset:20096
	s_waitcnt lgkmcnt(7)
	v_mfma_f32_16x16x32_bf16 v[128:131], v[226:229], v[12:15], v[24:27]
	v_exp_f32_e32 v74, v74
	v_mfma_f32_16x16x32_bf16 v[132:135], v[226:229], v[20:23], v[28:31]
	v_exp_f32_e32 v75, v75
	ds_read_b128 v[226:229], v179 offset:23424
	s_waitcnt lgkmcnt(7)
	v_mfma_f32_16x16x32_bf16 v[104:107], v[198:201], v[8:11], v[104:107]
	v_exp_f32_e32 v80, v80
	v_exp_f32_e32 v81, v81
	v_mfma_f32_16x16x32_bf16 v[108:111], v[198:201], v[16:19], v[108:111]
	v_exp_f32_e32 v82, v82
	s_waitcnt lgkmcnt(6)
	v_mfma_f32_16x16x32_bf16 v[112:115], v[202:205], v[8:11], v[112:115]
	v_exp_f32_e32 v83, v83
	v_mfma_f32_16x16x32_bf16 v[116:119], v[202:205], v[16:19], v[116:119]
	v_exp_f32_e32 v76, v76
	s_waitcnt lgkmcnt(5)
	v_mfma_f32_16x16x32_bf16 v[120:123], v[206:209], v[8:11], v[120:123]
	v_exp_f32_e32 v77, v77
	v_mfma_f32_16x16x32_bf16 v[124:127], v[206:209], v[16:19], v[124:127]
	v_exp_f32_e32 v78, v78
	v_exp_f32_e32 v79, v79
	s_waitcnt lgkmcnt(4)
	v_mfma_f32_16x16x32_bf16 v[128:131], v[210:213], v[8:11], v[128:131]
	v_exp_f32_e32 v84, v84
	v_mfma_f32_16x16x32_bf16 v[132:135], v[210:213], v[16:19], v[132:135]
	v_exp_f32_e32 v85, v85
	s_waitcnt lgkmcnt(3)
	v_mfma_f32_16x16x32_bf16 v[104:107], v[214:217], v[4:7], v[104:107]
	v_exp_f32_e32 v86, v86
	v_mfma_f32_16x16x32_bf16 v[108:111], v[214:217], v[0:3], v[108:111]
	v_exp_f32_e32 v87, v87
	s_waitcnt lgkmcnt(2)
	v_mfma_f32_16x16x32_bf16 v[112:115], v[218:221], v[4:7], v[112:115]
	v_cvt_pk_bf16_f32 v136, v72, v73
	v_cvt_pk_bf16_f32 v137, v74, v75
	v_mfma_f32_16x16x32_bf16 v[116:119], v[218:221], v[0:3], v[116:119]
	v_cvt_pk_bf16_f32 v138, v80, v81
	s_waitcnt lgkmcnt(1)
	v_mfma_f32_16x16x32_bf16 v[120:123], v[222:225], v[4:7], v[120:123]
	v_cvt_pk_bf16_f32 v139, v82, v83
	v_mfma_f32_16x16x32_bf16 v[124:127], v[222:225], v[0:3], v[124:127]
	v_cvt_pk_bf16_f32 v140, v76, v77
	s_waitcnt lgkmcnt(0)
	v_mfma_f32_16x16x32_bf16 v[128:131], v[226:229], v[4:7], v[128:131]
	v_cvt_pk_bf16_f32 v141, v78, v79
	v_mfma_f32_16x16x32_bf16 v[132:135], v[226:229], v[0:3], v[132:135]
	v_cvt_pk_bf16_f32 v142, v84, v85
	v_cvt_pk_bf16_f32 v143, v86, v87
	s_waitcnt lgkmcnt(0)
	s_barrier
; DEV float ex2(float x) { return __builtin_amdgcn_exp2f(x); }
; DEV void attn_item(const Params& p, int bl, int head, int q0, int nkeys, char* smem, int tid) {
;     ...
; #pragma unroll
;       for (int kk = 0; kk < 2; ++kk) {
;         bf16x8 pb[2];
; #pragma unroll
;         for (int qt = 0; qt < 2; ++qt) {
;           const float e0 = ex2(s[2 * kk][qt][0]), e1 = ex2(s[2 * kk][qt][1]), e2 = ex2(s[2 * kk][qt][2]), e3 = ex2(s[2 * kk][qt][3]);
;           const float e4 = ex2(s[2 * kk + 1][qt][0]), e5 = ex2(s[2 * kk + 1][qt][1]), e6 = ex2(s[2 * kk + 1][qt][2]), e7 = ex2(s[2 * kk + 1][qt][3]);
;           u32x4 cw = {pack2(e0, e1), pack2(e2, e3), pack2(e4, e5), pack2(e6, e7)};
;           pb[qt] = __builtin_bit_cast(bf16x8, cw);
;         }
;         lacc[0] = __builtin_amdgcn_mfma_f32_16x16x32_bf16(ones, pb[0], lacc[0], 0, 0, 0);
;         lacc[1] = __builtin_amdgcn_mfma_f32_16x16x32_bf16(ones, pb[1], lacc[1], 0, 0, 0);
; #pragma unroll
;         for (int dvf = 0; dvf < 4; ++dvf) {
;           const char* vp = vb + (dvf * 16 + fr) * VROW + (hh * 64 + kk * 32 + fq * 4) * 2;
;           const uint2 h0 = *(const uint2*)vp, h1 = *(const uint2*)(vp + 32);
;           u32x4 vw = {h0.x, h0.y, h1.x, h1.y};
;           const bf16x8 va = __builtin_bit_cast(bf16x8, vw);
;           o[dvf][0] = __builtin_amdgcn_mfma_f32_16x16x32_bf16(va, pb[0], o[dvf][0], 0, 0, 0);
;           o[dvf][1] = __builtin_amdgcn_mfma_f32_16x16x32_bf16(va, pb[1], o[dvf][1], 0, 0, 0);
;         }
	s_mov_b32 s18, s15
	s_mov_b32 s15, s12
	s_mov_b32 s12, s9
	s_mov_b32 s9, s18
	s_add_i32 s13, s13, 1
	global_load_dwordx4 v[230:233], v[164:165], off
	global_load_dwordx4 v[234:237], v[166:167], off
	global_load_dwordx4 v[238:241], v[168:169], off
	global_load_dwordx4 v[242:245], v[170:171], off
	global_load_dwordx4 v[246:249], v[172:173], off
	v_lshl_add_u64 v[164:165], v[164:165], 0, s[26:27]
	v_lshl_add_u64 v[166:167], v[166:167], 0, s[26:27]
	v_lshl_add_u64 v[168:169], v[168:169], 0, s[16:17]
	v_lshl_add_u64 v[170:171], v[170:171], 0, s[16:17]
	v_lshl_add_u64 v[172:173], v[172:173], 0, s[16:17]
	v_add_u32_e32 v184, s9, v190
	v_add_u32_e32 v185, s9, v191
	v_add_u32_e32 v186, s9, v192
	v_add_u32_e32 v187, s9, v160
	v_add_u32_e32 v188, s9, v162
	v_add3_u32 v180, s15, v176, v177
	ds_read_b64 v[198:199], v180 offset:26624
	ds_read_b64 v[200:201], v180 offset:26656
	ds_read_b64 v[202:203], v180 offset:30976
	ds_read_b64 v[204:205], v180 offset:31008
	ds_read_b64 v[206:207], v180 offset:35328
	ds_read_b64 v[208:209], v180 offset:35360
	ds_read_b64 v[210:211], v180 offset:39680
	ds_read_b64 v[212:213], v180 offset:39712
	ds_read_b64 v[214:215], v180 offset:26688
	ds_read_b64 v[216:217], v180 offset:26720
	ds_read_b64 v[218:219], v180 offset:31040
	ds_read_b64 v[220:221], v180 offset:31072
	ds_read_b64 v[222:223], v180 offset:35392
	ds_read_b64 v[224:225], v180 offset:35424
	ds_read_b64 v[226:227], v180 offset:39744
	ds_read_b64 v[228:229], v180 offset:39776
	v_mfma_f32_16x16x32_bf16 v[68:71], v[152:155], v[136:139], v[68:71]
	v_exp_f32_e32 v88, v88
	v_exp_f32_e32 v89, v89
	v_mfma_f32_16x16x32_bf16 v[56:59], v[152:155], v[140:143], v[56:59]
	v_exp_f32_e32 v90, v90
	v_exp_f32_e32 v91, v91
	s_waitcnt lgkmcnt(8)
	v_mfma_f32_16x16x32_bf16 v[32:35], v[198:201], v[136:139], v[32:35]
	v_exp_f32_e32 v96, v96
	v_exp_f32_e32 v97, v97
	v_mfma_f32_16x16x32_bf16 v[36:39], v[198:201], v[140:143], v[36:39]
	v_exp_f32_e32 v98, v98
	v_exp_f32_e32 v99, v99
	v_exp_f32_e32 v92, v92
	v_mfma_f32_16x16x32_bf16 v[40:43], v[202:205], v[136:139], v[40:43]
	v_exp_f32_e32 v93, v93
	v_exp_f32_e32 v94, v94
	v_mfma_f32_16x16x32_bf16 v[60:63], v[202:205], v[140:143], v[60:63]
	v_exp_f32_e32 v95, v95
	v_exp_f32_e32 v100, v100
	v_exp_f32_e32 v101, v101
	v_mfma_f32_16x16x32_bf16 v[44:47], v[206:209], v[136:139], v[44:47]
	v_exp_f32_e32 v102, v102
	v_exp_f32_e32 v103, v103
	v_mfma_f32_16x16x32_bf16 v[64:67], v[206:209], v[140:143], v[64:67]
	v_cvt_pk_bf16_f32 v144, v88, v89
	v_cvt_pk_bf16_f32 v145, v90, v91
	v_cvt_pk_bf16_f32 v146, v96, v97
	v_mfma_f32_16x16x32_bf16 v[48:51], v[210:213], v[136:139], v[48:51]
	v_cvt_pk_bf16_f32 v147, v98, v99
	v_cvt_pk_bf16_f32 v148, v92, v93
	v_mfma_f32_16x16x32_bf16 v[52:55], v[210:213], v[140:143], v[52:55]
	v_cvt_pk_bf16_f32 v149, v94, v95
	v_cvt_pk_bf16_f32 v150, v100, v101
	v_cvt_pk_bf16_f32 v151, v102, v103
	ds_read_b64 v[198:199], v180 offset:26752
	ds_read_b64 v[200:201], v180 offset:26784
	ds_read_b64 v[202:203], v180 offset:31104
	ds_read_b64 v[204:205], v180 offset:31136
	ds_read_b64 v[206:207], v180 offset:35456
	ds_read_b64 v[208:209], v180 offset:35488
	ds_read_b64 v[210:211], v180 offset:39808
	ds_read_b64 v[212:213], v180 offset:39840
	s_nop 1
	v_mfma_f32_16x16x32_bf16 v[68:71], v[152:155], v[144:147], v[68:71]
	v_exp_f32_e32 v104, v104
	v_exp_f32_e32 v105, v105
	v_mfma_f32_16x16x32_bf16 v[56:59], v[152:155], v[148:151], v[56:59]
	v_exp_f32_e32 v106, v106
	v_exp_f32_e32 v107, v107
	s_waitcnt lgkmcnt(8)
	v_mfma_f32_16x16x32_bf16 v[32:35], v[214:217], v[144:147], v[32:35]
	v_exp_f32_e32 v112, v112
	v_exp_f32_e32 v113, v113
	v_mfma_f32_16x16x32_bf16 v[36:39], v[214:217], v[148:151], v[36:39]
	v_exp_f32_e32 v114, v114
	v_exp_f32_e32 v115, v115
	v_exp_f32_e32 v108, v108
	v_mfma_f32_16x16x32_bf16 v[40:43], v[218:221], v[144:147], v[40:43]
	v_exp_f32_e32 v109, v109
	v_exp_f32_e32 v110, v110
	v_mfma_f32_16x16x32_bf16 v[60:63], v[218:221], v[148:151], v[60:63]
	v_exp_f32_e32 v111, v111
	v_exp_f32_e32 v116, v116
	v_exp_f32_e32 v117, v117
	v_mfma_f32_16x16x32_bf16 v[44:47], v[222:225], v[144:147], v[44:47]
	v_exp_f32_e32 v118, v118
	v_exp_f32_e32 v119, v119
	v_mfma_f32_16x16x32_bf16 v[64:67], v[222:225], v[148:151], v[64:67]
	v_cvt_pk_bf16_f32 v136, v104, v105
	v_cvt_pk_bf16_f32 v137, v106, v107
	v_cvt_pk_bf16_f32 v138, v112, v113
	v_mfma_f32_16x16x32_bf16 v[48:51], v[226:229], v[144:147], v[48:51]
	v_cvt_pk_bf16_f32 v139, v114, v115
	v_cvt_pk_bf16_f32 v140, v108, v109
	v_mfma_f32_16x16x32_bf16 v[52:55], v[226:229], v[148:151], v[52:55]
	v_cvt_pk_bf16_f32 v141, v110, v111
	v_cvt_pk_bf16_f32 v142, v116, v117
	v_cvt_pk_bf16_f32 v143, v118, v119
	ds_read_b64 v[214:215], v180 offset:26816
	ds_read_b64 v[216:217], v180 offset:26848
	ds_read_b64 v[218:219], v180 offset:31168
	ds_read_b64 v[220:221], v180 offset:31200
	ds_read_b64 v[222:223], v180 offset:35520
	ds_read_b64 v[224:225], v180 offset:35552
	ds_read_b64 v[226:227], v180 offset:39872
	ds_read_b64 v[228:229], v180 offset:39904
	s_nop 1
	v_mfma_f32_16x16x32_bf16 v[68:71], v[152:155], v[136:139], v[68:71]
	v_exp_f32_e32 v120, v120
	v_exp_f32_e32 v121, v121
	v_mfma_f32_16x16x32_bf16 v[56:59], v[152:155], v[140:143], v[56:59]
	v_exp_f32_e32 v122, v122
	v_exp_f32_e32 v123, v123
	s_waitcnt lgkmcnt(8)
; DEV float ex2(float x) { return __builtin_amdgcn_exp2f(x); }
; DEV void attn_item(const Params& p, int bl, int head, int q0, int nkeys, char* smem, int tid) {
;     ...
;     for (int hh = 0; hh < 2; ++hh) {
;       f32x4 s[4][2];
; #pragma unroll
;       for (int kf = 0; kf < 4; ++kf) {
; #pragma unroll
;         for (int ks = 0; ks < 3; ++ks) {
;           bf16x8 a = *(const bf16x8*)(kb + (hh * 64 + kf * 16 + fr) * KROW + ks * 64 + fq * 16);
;           s[kf][0] = __builtin_amdgcn_mfma_f32_16x16x32_bf16(a, qf[0][ks], ks == 0 ? negm[0] : s[kf][0], 0, 0, 0);
;           s[kf][1] = __builtin_amdgcn_mfma_f32_16x16x32_bf16(a, qf[1][ks], ks == 0 ? negm[1] : s[kf][1], 0, 0, 0);
;         }
;       }
; #pragma unroll
;       for (int kk = 0; kk < 2; ++kk) {
;         bf16x8 pb[2];
; #pragma unroll
;         for (int qt = 0; qt < 2; ++qt) {
;           const float e0 = ex2(s[2 * kk][qt][0]), e1 = ex2(s[2 * kk][qt][1]), e2 = ex2(s[2 * kk][qt][2]), e3 = ex2(s[2 * kk][qt][3]);
;           const float e4 = ex2(s[2 * kk + 1][qt][0]), e5 = ex2(s[2 * kk + 1][qt][1]), e6 = ex2(s[2 * kk + 1][qt][2]), e7 = ex2(s[2 * kk + 1][qt][3]);
;           u32x4 cw = {pack2(e0, e1), pack2(e2, e3), pack2(e4, e5), pack2(e6, e7)};
;           pb[qt] = __builtin_bit_cast(bf16x8, cw);
;         }
;         lacc[0] = __builtin_amdgcn_mfma_f32_16x16x32_bf16(ones, pb[0], lacc[0], 0, 0, 0);
;         lacc[1] = __builtin_amdgcn_mfma_f32_16x16x32_bf16(ones, pb[1], lacc[1], 0, 0, 0);
; #pragma unroll
;         for (int dvf = 0; dvf < 4; ++dvf) {
;           const char* vp = vb + (dvf * 16 + fr) * VROW + (hh * 64 + kk * 32 + fq * 4) * 2;
;           const uint2 h0 = *(const uint2*)vp, h1 = *(const uint2*)(vp + 32);
;           u32x4 vw = {h0.x, h0.y, h1.x, h1.y};
;           const bf16x8 va = __builtin_bit_cast(bf16x8, vw);
;           o[dvf][0] = __builtin_amdgcn_mfma_f32_16x16x32_bf16(va, pb[0], o[dvf][0], 0, 0, 0);
;           o[dvf][1] = __builtin_amdgcn_mfma_f32_16x16x32_bf16(va, pb[1], o[dvf][1], 0, 0, 0);
;         }
;       }
;     }
;     if (t + 1 < nt) {
;       char* nb = smem + ((t + 1) & 1) * ASTG;
; #pragma unroll
;       for (int i = 0; i < 3; ++i) *(u32x4*)(nb + koff[i]) = kr[i];
	v_mfma_f32_16x16x32_bf16 v[32:35], v[198:201], v[136:139], v[32:35]
	v_exp_f32_e32 v128, v128
	v_exp_f32_e32 v129, v129
	v_mfma_f32_16x16x32_bf16 v[36:39], v[198:201], v[140:143], v[36:39]
	v_exp_f32_e32 v130, v130
	v_exp_f32_e32 v131, v131
	v_exp_f32_e32 v124, v124
	v_mfma_f32_16x16x32_bf16 v[40:43], v[202:205], v[136:139], v[40:43]
	v_exp_f32_e32 v125, v125
	v_exp_f32_e32 v126, v126
	v_mfma_f32_16x16x32_bf16 v[60:63], v[202:205], v[140:143], v[60:63]
	v_exp_f32_e32 v127, v127
	v_exp_f32_e32 v132, v132
	v_exp_f32_e32 v133, v133
	v_mfma_f32_16x16x32_bf16 v[44:47], v[206:209], v[136:139], v[44:47]
	v_exp_f32_e32 v134, v134
	v_exp_f32_e32 v135, v135
	v_mfma_f32_16x16x32_bf16 v[64:67], v[206:209], v[140:143], v[64:67]
	v_cvt_pk_bf16_f32 v144, v120, v121
	v_cvt_pk_bf16_f32 v145, v122, v123
	v_cvt_pk_bf16_f32 v146, v128, v129
	v_mfma_f32_16x16x32_bf16 v[48:51], v[210:213], v[136:139], v[48:51]
	v_cvt_pk_bf16_f32 v147, v130, v131
	v_cvt_pk_bf16_f32 v148, v124, v125
	v_mfma_f32_16x16x32_bf16 v[52:55], v[210:213], v[140:143], v[52:55]
	v_cvt_pk_bf16_f32 v149, v126, v127
	v_cvt_pk_bf16_f32 v150, v132, v133
	v_cvt_pk_bf16_f32 v151, v134, v135
	s_nop 1
	v_mfma_f32_16x16x32_bf16 v[68:71], v[152:155], v[144:147], v[68:71]
	v_mfma_f32_16x16x32_bf16 v[56:59], v[152:155], v[148:151], v[56:59]
	s_waitcnt lgkmcnt(0)
	v_mfma_f32_16x16x32_bf16 v[32:35], v[214:217], v[144:147], v[32:35]
	v_mfma_f32_16x16x32_bf16 v[36:39], v[214:217], v[148:151], v[36:39]
	v_mfma_f32_16x16x32_bf16 v[40:43], v[218:221], v[144:147], v[40:43]
	v_mfma_f32_16x16x32_bf16 v[60:63], v[218:221], v[148:151], v[60:63]
	v_mfma_f32_16x16x32_bf16 v[44:47], v[222:225], v[144:147], v[44:47]
	v_mfma_f32_16x16x32_bf16 v[64:67], v[222:225], v[148:151], v[64:67]
	v_mfma_f32_16x16x32_bf16 v[48:51], v[226:229], v[144:147], v[48:51]
	v_mfma_f32_16x16x32_bf16 v[52:55], v[226:229], v[148:151], v[52:55]
	s_waitcnt vmcnt(0)
	ds_write_b128 v184, v[238:241]
	ds_write_b128 v185, v[242:245]
	ds_write_b128 v186, v[246:249]
	ds_write_b128 v187, v[230:233] offset:28672
	ds_write_b128 v188, v[234:237] offset:28672
	v_add3_u32 v179, s12, v156, v181
	ds_read_b128 v[198:201], v179
	ds_read_b128 v[202:205], v179 offset:3584
	ds_read_b128 v[206:209], v179 offset:7168
	ds_read_b128 v[210:213], v179 offset:10752
	ds_read_b128 v[214:217], v179 offset:64
	ds_read_b128 v[218:221], v179 offset:3648
	ds_read_b128 v[222:225], v179 offset:7232
	ds_read_b128 v[226:229], v179 offset:10816
	s_waitcnt lgkmcnt(7)
	v_mfma_f32_16x16x32_bf16 v[72:75], v[198:201], v[12:15], v[24:27]
	v_mfma_f32_16x16x32_bf16 v[76:79], v[198:201], v[20:23], v[28:31]
	ds_read_b128 v[198:201], v179 offset:128
	s_waitcnt lgkmcnt(7)
	v_mfma_f32_16x16x32_bf16 v[80:83], v[202:205], v[12:15], v[24:27]
	v_mfma_f32_16x16x32_bf16 v[84:87], v[202:205], v[20:23], v[28:31]
	ds_read_b128 v[202:205], v179 offset:3712
	s_waitcnt lgkmcnt(7)
	v_mfma_f32_16x16x32_bf16 v[88:91], v[206:209], v[12:15], v[24:27]
	v_mfma_f32_16x16x32_bf16 v[92:95], v[206:209], v[20:23], v[28:31]
	ds_read_b128 v[206:209], v179 offset:7296
	s_waitcnt lgkmcnt(7)
	v_mfma_f32_16x16x32_bf16 v[96:99], v[210:213], v[12:15], v[24:27]
	v_mfma_f32_16x16x32_bf16 v[100:103], v[210:213], v[20:23], v[28:31]
	ds_read_b128 v[210:213], v179 offset:10880
	s_waitcnt lgkmcnt(7)
	v_mfma_f32_16x16x32_bf16 v[72:75], v[214:217], v[8:11], v[72:75]
	v_mfma_f32_16x16x32_bf16 v[76:79], v[214:217], v[16:19], v[76:79]
	ds_read_b128 v[214:217], v179 offset:14336
	s_waitcnt lgkmcnt(7)
	v_mfma_f32_16x16x32_bf16 v[80:83], v[218:221], v[8:11], v[80:83]
	v_mfma_f32_16x16x32_bf16 v[84:87], v[218:221], v[16:19], v[84:87]
	ds_read_b128 v[218:221], v179 offset:17920
	s_waitcnt lgkmcnt(7)
	v_mfma_f32_16x16x32_bf16 v[88:91], v[222:225], v[8:11], v[88:91]
	v_mfma_f32_16x16x32_bf16 v[92:95], v[222:225], v[16:19], v[92:95]
	ds_read_b128 v[222:225], v179 offset:21504
	s_waitcnt lgkmcnt(7)
	v_mfma_f32_16x16x32_bf16 v[96:99], v[226:229], v[8:11], v[96:99]
	v_mfma_f32_16x16x32_bf16 v[100:103], v[226:229], v[16:19], v[100:103]
	ds_read_b128 v[226:229], v179 offset:25088
	s_waitcnt lgkmcnt(7)
	v_mfma_f32_16x16x32_bf16 v[72:75], v[198:201], v[4:7], v[72:75]
	v_mfma_f32_16x16x32_bf16 v[76:79], v[198:201], v[0:3], v[76:79]
	ds_read_b128 v[198:201], v179 offset:14400
	s_waitcnt lgkmcnt(7)
	v_mfma_f32_16x16x32_bf16 v[80:83], v[202:205], v[4:7], v[80:83]
	v_mfma_f32_16x16x32_bf16 v[84:87], v[202:205], v[0:3], v[84:87]
	ds_read_b128 v[202:205], v179 offset:17984
	s_waitcnt lgkmcnt(7)
	v_mfma_f32_16x16x32_bf16 v[88:91], v[206:209], v[4:7], v[88:91]
	v_mfma_f32_16x16x32_bf16 v[92:95], v[206:209], v[0:3], v[92:95]
	ds_read_b128 v[206:209], v179 offset:21568
	s_waitcnt lgkmcnt(7)
	v_mfma_f32_16x16x32_bf16 v[96:99], v[210:213], v[4:7], v[96:99]
	v_mfma_f32_16x16x32_bf16 v[100:103], v[210:213], v[0:3], v[100:103]
	ds_read_b128 v[210:213], v179 offset:25152
	s_waitcnt lgkmcnt(7)
	v_mfma_f32_16x16x32_bf16 v[104:107], v[214:217], v[12:15], v[24:27]
	v_mfma_f32_16x16x32_bf16 v[108:111], v[214:217], v[20:23], v[28:31]
	ds_read_b128 v[214:217], v179 offset:14464
	s_waitcnt lgkmcnt(7)
	v_mfma_f32_16x16x32_bf16 v[112:115], v[218:221], v[12:15], v[24:27]
	v_mfma_f32_16x16x32_bf16 v[116:119], v[218:221], v[20:23], v[28:31]
	ds_read_b128 v[218:221], v179 offset:18048
	s_waitcnt lgkmcnt(7)
	v_mfma_f32_16x16x32_bf16 v[120:123], v[222:225], v[12:15], v[24:27]
	v_exp_f32_e32 v72, v72
	v_mfma_f32_16x16x32_bf16 v[124:127], v[222:225], v[20:23], v[28:31]
	v_exp_f32_e32 v73, v73
	ds_read_b128 v[222:225], v179 offset:21632
	s_waitcnt lgkmcnt(7)
	v_mfma_f32_16x16x32_bf16 v[128:131], v[226:229], v[12:15], v[24:27]
	v_exp_f32_e32 v74, v74
	v_mfma_f32_16x16x32_bf16 v[132:135], v[226:229], v[20:23], v[28:31]
	v_exp_f32_e32 v75, v75
	ds_read_b128 v[226:229], v179 offset:25216
	s_waitcnt lgkmcnt(7)
; DEV float ex2(float x) { return __builtin_amdgcn_exp2f(x); }
; DEV void attn_item(const Params& p, int bl, int head, int q0, int nkeys, char* smem, int tid) {
;     ...
; #pragma unroll
;       for (int kk = 0; kk < 2; ++kk) {
;         bf16x8 pb[2];
; #pragma unroll
;         for (int qt = 0; qt < 2; ++qt) {
;           const float e0 = ex2(s[2 * kk][qt][0]), e1 = ex2(s[2 * kk][qt][1]), e2 = ex2(s[2 * kk][qt][2]), e3 = ex2(s[2 * kk][qt][3]);
;           const float e4 = ex2(s[2 * kk + 1][qt][0]), e5 = ex2(s[2 * kk + 1][qt][1]), e6 = ex2(s[2 * kk + 1][qt][2]), e7 = ex2(s[2 * kk + 1][qt][3]);
;           u32x4 cw = {pack2(e0, e1), pack2(e2, e3), pack2(e4, e5), pack2(e6, e7)};
;           pb[qt] = __builtin_bit_cast(bf16x8, cw);
;         }
;         lacc[0] = __builtin_amdgcn_mfma_f32_16x16x32_bf16(ones, pb[0], lacc[0], 0, 0, 0);
;         lacc[1] = __builtin_amdgcn_mfma_f32_16x16x32_bf16(ones, pb[1], lacc[1], 0, 0, 0);
; #pragma unroll
;         for (int dvf = 0; dvf < 4; ++dvf) {
;           const char* vp = vb + (dvf * 16 + fr) * VROW + (hh * 64 + kk * 32 + fq * 4) * 2;
;           const uint2 h0 = *(const uint2*)vp, h1 = *(const uint2*)(vp + 32);
;           u32x4 vw = {h0.x, h0.y, h1.x, h1.y};
;           const bf16x8 va = __builtin_bit_cast(bf16x8, vw);
;           o[dvf][0] = __builtin_amdgcn_mfma_f32_16x16x32_bf16(va, pb[0], o[dvf][0], 0, 0, 0);
;           o[dvf][1] = __builtin_amdgcn_mfma_f32_16x16x32_bf16(va, pb[1], o[dvf][1], 0, 0, 0);
;         }
;       }
;     }
;     if (t + 1 < nt) {
;       char* nb = smem + ((t + 1) & 1) * ASTG;
; #pragma unroll
;       for (int i = 0; i < 3; ++i) *(u32x4*)(nb + koff[i]) = kr[i];
; #pragma unroll
;       for (int i = 0; i < 2; ++i) *(u32x4*)(nb + KBYTES + voffl[i]) = vr[i];
;     }
;     __syncthreads();
	v_mfma_f32_16x16x32_bf16 v[104:107], v[198:201], v[8:11], v[104:107]
	v_exp_f32_e32 v80, v80
	v_exp_f32_e32 v81, v81
	v_mfma_f32_16x16x32_bf16 v[108:111], v[198:201], v[16:19], v[108:111]
	v_exp_f32_e32 v82, v82
	s_waitcnt lgkmcnt(6)
	v_mfma_f32_16x16x32_bf16 v[112:115], v[202:205], v[8:11], v[112:115]
	v_exp_f32_e32 v83, v83
	v_mfma_f32_16x16x32_bf16 v[116:119], v[202:205], v[16:19], v[116:119]
	v_exp_f32_e32 v76, v76
	s_waitcnt lgkmcnt(5)
	v_mfma_f32_16x16x32_bf16 v[120:123], v[206:209], v[8:11], v[120:123]
	v_exp_f32_e32 v77, v77
	v_mfma_f32_16x16x32_bf16 v[124:127], v[206:209], v[16:19], v[124:127]
	v_exp_f32_e32 v78, v78
	v_exp_f32_e32 v79, v79
	s_waitcnt lgkmcnt(4)
	v_mfma_f32_16x16x32_bf16 v[128:131], v[210:213], v[8:11], v[128:131]
	v_exp_f32_e32 v84, v84
	v_mfma_f32_16x16x32_bf16 v[132:135], v[210:213], v[16:19], v[132:135]
	v_exp_f32_e32 v85, v85
	s_waitcnt lgkmcnt(3)
	v_mfma_f32_16x16x32_bf16 v[104:107], v[214:217], v[4:7], v[104:107]
	v_exp_f32_e32 v86, v86
	v_mfma_f32_16x16x32_bf16 v[108:111], v[214:217], v[0:3], v[108:111]
	v_exp_f32_e32 v87, v87
	s_waitcnt lgkmcnt(2)
	v_mfma_f32_16x16x32_bf16 v[112:115], v[218:221], v[4:7], v[112:115]
	v_cvt_pk_bf16_f32 v136, v72, v73
	v_cvt_pk_bf16_f32 v137, v74, v75
	v_mfma_f32_16x16x32_bf16 v[116:119], v[218:221], v[0:3], v[116:119]
	v_cvt_pk_bf16_f32 v138, v80, v81
	s_waitcnt lgkmcnt(1)
	v_mfma_f32_16x16x32_bf16 v[120:123], v[222:225], v[4:7], v[120:123]
	v_cvt_pk_bf16_f32 v139, v82, v83
	v_mfma_f32_16x16x32_bf16 v[124:127], v[222:225], v[0:3], v[124:127]
	v_cvt_pk_bf16_f32 v140, v76, v77
	s_waitcnt lgkmcnt(0)
	v_mfma_f32_16x16x32_bf16 v[128:131], v[226:229], v[4:7], v[128:131]
	v_cvt_pk_bf16_f32 v141, v78, v79
	v_mfma_f32_16x16x32_bf16 v[132:135], v[226:229], v[0:3], v[132:135]
	v_cvt_pk_bf16_f32 v142, v84, v85
	v_cvt_pk_bf16_f32 v143, v86, v87
	s_waitcnt lgkmcnt(0)
	s_barrier
	s_mov_b32 s18, s15
	s_mov_b32 s15, s12
	s_mov_b32 s12, s9
	s_mov_b32 s9, s18
	s_add_i32 s13, s13, 1
.Lattn_b_loop:
	global_load_dwordx4 v[230:233], v[164:165], off
	global_load_dwordx4 v[234:237], v[166:167], off
	global_load_dwordx4 v[238:241], v[168:169], off
	global_load_dwordx4 v[242:245], v[170:171], off
	global_load_dwordx4 v[246:249], v[172:173], off
	v_lshl_add_u64 v[164:165], v[164:165], 0, s[26:27]
	v_lshl_add_u64 v[166:167], v[166:167], 0, s[26:27]
	v_lshl_add_u64 v[168:169], v[168:169], 0, s[16:17]
	v_lshl_add_u64 v[170:171], v[170:171], 0, s[16:17]
	v_lshl_add_u64 v[172:173], v[172:173], 0, s[16:17]
	v_add_u32_e32 v184, s9, v190
	v_add_u32_e32 v185, s9, v191
	v_add_u32_e32 v186, s9, v192
	v_add_u32_e32 v187, s9, v160
	v_add_u32_e32 v188, s9, v162
	v_add3_u32 v180, s15, v176, v177
	ds_read_b64 v[198:199], v180 offset:28672
	ds_read_b64 v[200:201], v180 offset:28704
	ds_read_b64 v[202:203], v180 offset:33024
	ds_read_b64 v[204:205], v180 offset:33056
	ds_read_b64 v[206:207], v180 offset:37376
	ds_read_b64 v[208:209], v180 offset:37408
	ds_read_b64 v[210:211], v180 offset:41728
	ds_read_b64 v[212:213], v180 offset:41760
	ds_read_b64 v[214:215], v180 offset:28736
	ds_read_b64 v[216:217], v180 offset:28768
	ds_read_b64 v[218:219], v180 offset:33088
	ds_read_b64 v[220:221], v180 offset:33120
	ds_read_b64 v[222:223], v180 offset:37440
	ds_read_b64 v[224:225], v180 offset:37472
	ds_read_b64 v[226:227], v180 offset:41792
	ds_read_b64 v[228:229], v180 offset:41824
	v_mfma_f32_16x16x32_bf16 v[68:71], v[152:155], v[136:139], v[68:71]
	v_exp_f32_e32 v88, v88
	v_exp_f32_e32 v89, v89
	v_mfma_f32_16x16x32_bf16 v[56:59], v[152:155], v[140:143], v[56:59]
	v_exp_f32_e32 v90, v90
	v_exp_f32_e32 v91, v91
	s_waitcnt lgkmcnt(8)
	v_mfma_f32_16x16x32_bf16 v[32:35], v[198:201], v[136:139], v[32:35]
	v_exp_f32_e32 v96, v96
	v_exp_f32_e32 v97, v97
	v_mfma_f32_16x16x32_bf16 v[36:39], v[198:201], v[140:143], v[36:39]
	v_exp_f32_e32 v98, v98
	v_exp_f32_e32 v99, v99
	v_exp_f32_e32 v92, v92
	v_mfma_f32_16x16x32_bf16 v[40:43], v[202:205], v[136:139], v[40:43]
	v_exp_f32_e32 v93, v93
	v_exp_f32_e32 v94, v94
	v_mfma_f32_16x16x32_bf16 v[60:63], v[202:205], v[140:143], v[60:63]
	v_exp_f32_e32 v95, v95
	v_exp_f32_e32 v100, v100
	v_exp_f32_e32 v101, v101
	v_mfma_f32_16x16x32_bf16 v[44:47], v[206:209], v[136:139], v[44:47]
	v_exp_f32_e32 v102, v102
	v_exp_f32_e32 v103, v103
	v_mfma_f32_16x16x32_bf16 v[64:67], v[206:209], v[140:143], v[64:67]
	v_cvt_pk_bf16_f32 v144, v88, v89
	v_cvt_pk_bf16_f32 v145, v90, v91
	v_cvt_pk_bf16_f32 v146, v96, v97
	v_mfma_f32_16x16x32_bf16 v[48:51], v[210:213], v[136:139], v[48:51]
	v_cvt_pk_bf16_f32 v147, v98, v99
	v_cvt_pk_bf16_f32 v148, v92, v93
	v_mfma_f32_16x16x32_bf16 v[52:55], v[210:213], v[140:143], v[52:55]
	v_cvt_pk_bf16_f32 v149, v94, v95
	v_cvt_pk_bf16_f32 v150, v100, v101
	v_cvt_pk_bf16_f32 v151, v102, v103
	ds_read_b64 v[198:199], v180 offset:28800
	ds_read_b64 v[200:201], v180 offset:28832
	ds_read_b64 v[202:203], v180 offset:33152
	ds_read_b64 v[204:205], v180 offset:33184
	ds_read_b64 v[206:207], v180 offset:37504
	ds_read_b64 v[208:209], v180 offset:37536
	ds_read_b64 v[210:211], v180 offset:41856
	ds_read_b64 v[212:213], v180 offset:41888
	s_nop 1
	v_mfma_f32_16x16x32_bf16 v[68:71], v[152:155], v[144:147], v[68:71]
	v_exp_f32_e32 v104, v104
	v_exp_f32_e32 v105, v105
	v_mfma_f32_16x16x32_bf16 v[56:59], v[152:155], v[148:151], v[56:59]
	v_exp_f32_e32 v106, v106
	v_exp_f32_e32 v107, v107
	s_waitcnt lgkmcnt(8)
; DEV float ex2(float x) { return __builtin_amdgcn_exp2f(x); }
; DEV void attn_item(const Params& p, int bl, int head, int q0, int nkeys, char* smem, int tid) {
;     ...
;     for (int hh = 0; hh < 2; ++hh) {
;       f32x4 s[4][2];
; #pragma unroll
;       for (int kf = 0; kf < 4; ++kf) {
; #pragma unroll
;         for (int ks = 0; ks < 3; ++ks) {
;           bf16x8 a = *(const bf16x8*)(kb + (hh * 64 + kf * 16 + fr) * KROW + ks * 64 + fq * 16);
;           s[kf][0] = __builtin_amdgcn_mfma_f32_16x16x32_bf16(a, qf[0][ks], ks == 0 ? negm[0] : s[kf][0], 0, 0, 0);
;           s[kf][1] = __builtin_amdgcn_mfma_f32_16x16x32_bf16(a, qf[1][ks], ks == 0 ? negm[1] : s[kf][1], 0, 0, 0);
;         }
;       }
; #pragma unroll
;       for (int kk = 0; kk < 2; ++kk) {
;         bf16x8 pb[2];
; #pragma unroll
;         for (int qt = 0; qt < 2; ++qt) {
;           const float e0 = ex2(s[2 * kk][qt][0]), e1 = ex2(s[2 * kk][qt][1]), e2 = ex2(s[2 * kk][qt][2]), e3 = ex2(s[2 * kk][qt][3]);
;           const float e4 = ex2(s[2 * kk + 1][qt][0]), e5 = ex2(s[2 * kk + 1][qt][1]), e6 = ex2(s[2 * kk + 1][qt][2]), e7 = ex2(s[2 * kk + 1][qt][3]);
;           u32x4 cw = {pack2(e0, e1), pack2(e2, e3), pack2(e4, e5), pack2(e6, e7)};
;           pb[qt] = __builtin_bit_cast(bf16x8, cw);
;         }
;         lacc[0] = __builtin_amdgcn_mfma_f32_16x16x32_bf16(ones, pb[0], lacc[0], 0, 0, 0);
;         lacc[1] = __builtin_amdgcn_mfma_f32_16x16x32_bf16(ones, pb[1], lacc[1], 0, 0, 0);
; #pragma unroll
;         for (int dvf = 0; dvf < 4; ++dvf) {
;           const char* vp = vb + (dvf * 16 + fr) * VROW + (hh * 64 + kk * 32 + fq * 4) * 2;
;           const uint2 h0 = *(const uint2*)vp, h1 = *(const uint2*)(vp + 32);
;           u32x4 vw = {h0.x, h0.y, h1.x, h1.y};
;           const bf16x8 va = __builtin_bit_cast(bf16x8, vw);
;           o[dvf][0] = __builtin_amdgcn_mfma_f32_16x16x32_bf16(va, pb[0], o[dvf][0], 0, 0, 0);
;           o[dvf][1] = __builtin_amdgcn_mfma_f32_16x16x32_bf16(va, pb[1], o[dvf][1], 0, 0, 0);
;         }
;       }
;     }
;     if (t + 1 < nt) {
;       char* nb = smem + ((t + 1) & 1) * ASTG;
; #pragma unroll
;       for (int i = 0; i < 3; ++i) *(u32x4*)(nb + koff[i]) = kr[i];
	v_mfma_f32_16x16x32_bf16 v[32:35], v[214:217], v[144:147], v[32:35]
	v_exp_f32_e32 v112, v112
	v_exp_f32_e32 v113, v113
	v_mfma_f32_16x16x32_bf16 v[36:39], v[214:217], v[148:151], v[36:39]
	v_exp_f32_e32 v114, v114
	v_exp_f32_e32 v115, v115
	v_exp_f32_e32 v108, v108
	v_mfma_f32_16x16x32_bf16 v[40:43], v[218:221], v[144:147], v[40:43]
	v_exp_f32_e32 v109, v109
	v_exp_f32_e32 v110, v110
	v_mfma_f32_16x16x32_bf16 v[60:63], v[218:221], v[148:151], v[60:63]
	v_exp_f32_e32 v111, v111
	v_exp_f32_e32 v116, v116
	v_exp_f32_e32 v117, v117
	v_mfma_f32_16x16x32_bf16 v[44:47], v[222:225], v[144:147], v[44:47]
	v_exp_f32_e32 v118, v118
	v_exp_f32_e32 v119, v119
	v_mfma_f32_16x16x32_bf16 v[64:67], v[222:225], v[148:151], v[64:67]
	v_cvt_pk_bf16_f32 v136, v104, v105
	v_cvt_pk_bf16_f32 v137, v106, v107
	v_cvt_pk_bf16_f32 v138, v112, v113
	v_mfma_f32_16x16x32_bf16 v[48:51], v[226:229], v[144:147], v[48:51]
	v_cvt_pk_bf16_f32 v139, v114, v115
	v_cvt_pk_bf16_f32 v140, v108, v109
	v_mfma_f32_16x16x32_bf16 v[52:55], v[226:229], v[148:151], v[52:55]
	v_cvt_pk_bf16_f32 v141, v110, v111
	v_cvt_pk_bf16_f32 v142, v116, v117
	v_cvt_pk_bf16_f32 v143, v118, v119
	ds_read_b64 v[214:215], v180 offset:28864
	ds_read_b64 v[216:217], v180 offset:28896
	ds_read_b64 v[218:219], v180 offset:33216
	ds_read_b64 v[220:221], v180 offset:33248
	ds_read_b64 v[222:223], v180 offset:37568
	ds_read_b64 v[224:225], v180 offset:37600
	ds_read_b64 v[226:227], v180 offset:41920
	ds_read_b64 v[228:229], v180 offset:41952
	s_nop 1
	v_mfma_f32_16x16x32_bf16 v[68:71], v[152:155], v[136:139], v[68:71]
	v_exp_f32_e32 v120, v120
	v_exp_f32_e32 v121, v121
	v_mfma_f32_16x16x32_bf16 v[56:59], v[152:155], v[140:143], v[56:59]
	v_exp_f32_e32 v122, v122
	v_exp_f32_e32 v123, v123
	s_waitcnt lgkmcnt(8)
	v_mfma_f32_16x16x32_bf16 v[32:35], v[198:201], v[136:139], v[32:35]
	v_exp_f32_e32 v128, v128
	v_exp_f32_e32 v129, v129
	v_mfma_f32_16x16x32_bf16 v[36:39], v[198:201], v[140:143], v[36:39]
	v_exp_f32_e32 v130, v130
	v_exp_f32_e32 v131, v131
	v_exp_f32_e32 v124, v124
	v_mfma_f32_16x16x32_bf16 v[40:43], v[202:205], v[136:139], v[40:43]
	v_exp_f32_e32 v125, v125
	v_exp_f32_e32 v126, v126
	v_mfma_f32_16x16x32_bf16 v[60:63], v[202:205], v[140:143], v[60:63]
	v_exp_f32_e32 v127, v127
	v_exp_f32_e32 v132, v132
	v_exp_f32_e32 v133, v133
	v_mfma_f32_16x16x32_bf16 v[44:47], v[206:209], v[136:139], v[44:47]
	v_exp_f32_e32 v134, v134
	v_exp_f32_e32 v135, v135
	v_mfma_f32_16x16x32_bf16 v[64:67], v[206:209], v[140:143], v[64:67]
	v_cvt_pk_bf16_f32 v144, v120, v121
	v_cvt_pk_bf16_f32 v145, v122, v123
	v_cvt_pk_bf16_f32 v146, v128, v129
	v_mfma_f32_16x16x32_bf16 v[48:51], v[210:213], v[136:139], v[48:51]
	v_cvt_pk_bf16_f32 v147, v130, v131
	v_cvt_pk_bf16_f32 v148, v124, v125
	v_mfma_f32_16x16x32_bf16 v[52:55], v[210:213], v[140:143], v[52:55]
	v_cvt_pk_bf16_f32 v149, v126, v127
	v_cvt_pk_bf16_f32 v150, v132, v133
	v_cvt_pk_bf16_f32 v151, v134, v135
	s_nop 1
	v_mfma_f32_16x16x32_bf16 v[68:71], v[152:155], v[144:147], v[68:71]
	v_mfma_f32_16x16x32_bf16 v[56:59], v[152:155], v[148:151], v[56:59]
	s_waitcnt lgkmcnt(0)
	v_mfma_f32_16x16x32_bf16 v[32:35], v[214:217], v[144:147], v[32:35]
	v_mfma_f32_16x16x32_bf16 v[36:39], v[214:217], v[148:151], v[36:39]
	v_mfma_f32_16x16x32_bf16 v[40:43], v[218:221], v[144:147], v[40:43]
	v_mfma_f32_16x16x32_bf16 v[60:63], v[218:221], v[148:151], v[60:63]
	v_mfma_f32_16x16x32_bf16 v[44:47], v[222:225], v[144:147], v[44:47]
	v_mfma_f32_16x16x32_bf16 v[64:67], v[222:225], v[148:151], v[64:67]
	v_mfma_f32_16x16x32_bf16 v[48:51], v[226:229], v[144:147], v[48:51]
	v_mfma_f32_16x16x32_bf16 v[52:55], v[226:229], v[148:151], v[52:55]
	s_waitcnt vmcnt(0)
	ds_write_b128 v184, v[238:241]
	ds_write_b128 v185, v[242:245]
	ds_write_b128 v186, v[246:249]
	ds_write_b128 v187, v[230:233] offset:28672
	ds_write_b128 v188, v[234:237] offset:28672
	v_add3_u32 v179, s12, v156, v181
	ds_read_b128 v[198:201], v179
	ds_read_b128 v[202:205], v179 offset:3584
	ds_read_b128 v[206:209], v179 offset:7168
	ds_read_b128 v[210:213], v179 offset:10752
	ds_read_b128 v[214:217], v179 offset:64
	ds_read_b128 v[218:221], v179 offset:3648
	ds_read_b128 v[222:225], v179 offset:7232
	ds_read_b128 v[226:229], v179 offset:10816
	s_waitcnt lgkmcnt(7)
	v_mfma_f32_16x16x32_bf16 v[72:75], v[198:201], v[12:15], v[24:27]
	v_mfma_f32_16x16x32_bf16 v[76:79], v[198:201], v[20:23], v[28:31]
	ds_read_b128 v[198:201], v179 offset:128
	s_waitcnt lgkmcnt(7)
	v_mfma_f32_16x16x32_bf16 v[80:83], v[202:205], v[12:15], v[24:27]
	v_mfma_f32_16x16x32_bf16 v[84:87], v[202:205], v[20:23], v[28:31]
	ds_read_b128 v[202:205], v179 offset:3712
	s_waitcnt lgkmcnt(7)
	v_mfma_f32_16x16x32_bf16 v[88:91], v[206:209], v[12:15], v[24:27]
	v_mfma_f32_16x16x32_bf16 v[92:95], v[206:209], v[20:23], v[28:31]
	ds_read_b128 v[206:209], v179 offset:7296
	s_waitcnt lgkmcnt(7)
	v_mfma_f32_16x16x32_bf16 v[96:99], v[210:213], v[12:15], v[24:27]
	v_mfma_f32_16x16x32_bf16 v[100:103], v[210:213], v[20:23], v[28:31]
	ds_read_b128 v[210:213], v179 offset:10880
	s_waitcnt lgkmcnt(7)
	v_mfma_f32_16x16x32_bf16 v[72:75], v[214:217], v[8:11], v[72:75]
	v_mfma_f32_16x16x32_bf16 v[76:79], v[214:217], v[16:19], v[76:79]
	ds_read_b128 v[214:217], v179 offset:14336
	s_waitcnt lgkmcnt(7)
	v_mfma_f32_16x16x32_bf16 v[80:83], v[218:221], v[8:11], v[80:83]
	v_mfma_f32_16x16x32_bf16 v[84:87], v[218:221], v[16:19], v[84:87]
	ds_read_b128 v[218:221], v179 offset:17920
	s_waitcnt lgkmcnt(7)
	v_mfma_f32_16x16x32_bf16 v[88:91], v[222:225], v[8:11], v[88:91]
	v_mfma_f32_16x16x32_bf16 v[92:95], v[222:225], v[16:19], v[92:95]
	ds_read_b128 v[222:225], v179 offset:21504
	s_waitcnt lgkmcnt(7)
; DEV float ex2(float x) { return __builtin_amdgcn_exp2f(x); }
; DEV void attn_item(const Params& p, int bl, int head, int q0, int nkeys, char* smem, int tid) {
;     ...
;     for (int hh = 0; hh < 2; ++hh) {
;       f32x4 s[4][2];
; #pragma unroll
;       for (int kf = 0; kf < 4; ++kf) {
; #pragma unroll
;         for (int ks = 0; ks < 3; ++ks) {
;           bf16x8 a = *(const bf16x8*)(kb + (hh * 64 + kf * 16 + fr) * KROW + ks * 64 + fq * 16);
;           s[kf][0] = __builtin_amdgcn_mfma_f32_16x16x32_bf16(a, qf[0][ks], ks == 0 ? negm[0] : s[kf][0], 0, 0, 0);
;           s[kf][1] = __builtin_amdgcn_mfma_f32_16x16x32_bf16(a, qf[1][ks], ks == 0 ? negm[1] : s[kf][1], 0, 0, 0);
;         }
;       }
; #pragma unroll
;       for (int kk = 0; kk < 2; ++kk) {
;         bf16x8 pb[2];
; #pragma unroll
;         for (int qt = 0; qt < 2; ++qt) {
;           const float e0 = ex2(s[2 * kk][qt][0]), e1 = ex2(s[2 * kk][qt][1]), e2 = ex2(s[2 * kk][qt][2]), e3 = ex2(s[2 * kk][qt][3]);
;           const float e4 = ex2(s[2 * kk + 1][qt][0]), e5 = ex2(s[2 * kk + 1][qt][1]), e6 = ex2(s[2 * kk + 1][qt][2]), e7 = ex2(s[2 * kk + 1][qt][3]);
;           u32x4 cw = {pack2(e0, e1), pack2(e2, e3), pack2(e4, e5), pack2(e6, e7)};
;           pb[qt] = __builtin_bit_cast(bf16x8, cw);
;         }
;         lacc[0] = __builtin_amdgcn_mfma_f32_16x16x32_bf16(ones, pb[0], lacc[0], 0, 0, 0);
;         lacc[1] = __builtin_amdgcn_mfma_f32_16x16x32_bf16(ones, pb[1], lacc[1], 0, 0, 0);
; #pragma unroll
;         for (int dvf = 0; dvf < 4; ++dvf) {
;           const char* vp = vb + (dvf * 16 + fr) * VROW + (hh * 64 + kk * 32 + fq * 4) * 2;
;           const uint2 h0 = *(const uint2*)vp, h1 = *(const uint2*)(vp + 32);
;           u32x4 vw = {h0.x, h0.y, h1.x, h1.y};
;           const bf16x8 va = __builtin_bit_cast(bf16x8, vw);
;           o[dvf][0] = __builtin_amdgcn_mfma_f32_16x16x32_bf16(va, pb[0], o[dvf][0], 0, 0, 0);
;           o[dvf][1] = __builtin_amdgcn_mfma_f32_16x16x32_bf16(va, pb[1], o[dvf][1], 0, 0, 0);
;         }
;       }
;     }
;     if (t + 1 < nt) {
;       char* nb = smem + ((t + 1) & 1) * ASTG;
; #pragma unroll
;       for (int i = 0; i < 3; ++i) *(u32x4*)(nb + koff[i]) = kr[i];
; #pragma unroll
;       for (int i = 0; i < 2; ++i) *(u32x4*)(nb + KBYTES + voffl[i]) = vr[i];
;     }
;     __syncthreads();
	v_mfma_f32_16x16x32_bf16 v[96:99], v[226:229], v[8:11], v[96:99]
	v_mfma_f32_16x16x32_bf16 v[100:103], v[226:229], v[16:19], v[100:103]
	ds_read_b128 v[226:229], v179 offset:25088
	s_waitcnt lgkmcnt(7)
	v_mfma_f32_16x16x32_bf16 v[72:75], v[198:201], v[4:7], v[72:75]
	v_mfma_f32_16x16x32_bf16 v[76:79], v[198:201], v[0:3], v[76:79]
	ds_read_b128 v[198:201], v179 offset:14400
	s_waitcnt lgkmcnt(7)
	v_mfma_f32_16x16x32_bf16 v[80:83], v[202:205], v[4:7], v[80:83]
	v_mfma_f32_16x16x32_bf16 v[84:87], v[202:205], v[0:3], v[84:87]
	ds_read_b128 v[202:205], v179 offset:17984
	s_waitcnt lgkmcnt(7)
	v_mfma_f32_16x16x32_bf16 v[88:91], v[206:209], v[4:7], v[88:91]
	v_mfma_f32_16x16x32_bf16 v[92:95], v[206:209], v[0:3], v[92:95]
	ds_read_b128 v[206:209], v179 offset:21568
	s_waitcnt lgkmcnt(7)
	v_mfma_f32_16x16x32_bf16 v[96:99], v[210:213], v[4:7], v[96:99]
	v_mfma_f32_16x16x32_bf16 v[100:103], v[210:213], v[0:3], v[100:103]
	ds_read_b128 v[210:213], v179 offset:25152
	s_waitcnt lgkmcnt(7)
	v_mfma_f32_16x16x32_bf16 v[104:107], v[214:217], v[12:15], v[24:27]
	v_mfma_f32_16x16x32_bf16 v[108:111], v[214:217], v[20:23], v[28:31]
	ds_read_b128 v[214:217], v179 offset:14464
	s_waitcnt lgkmcnt(7)
	v_mfma_f32_16x16x32_bf16 v[112:115], v[218:221], v[12:15], v[24:27]
	v_mfma_f32_16x16x32_bf16 v[116:119], v[218:221], v[20:23], v[28:31]
	ds_read_b128 v[218:221], v179 offset:18048
	s_waitcnt lgkmcnt(7)
	v_mfma_f32_16x16x32_bf16 v[120:123], v[222:225], v[12:15], v[24:27]
	v_exp_f32_e32 v72, v72
	v_mfma_f32_16x16x32_bf16 v[124:127], v[222:225], v[20:23], v[28:31]
	v_exp_f32_e32 v73, v73
	ds_read_b128 v[222:225], v179 offset:21632
	s_waitcnt lgkmcnt(7)
	v_mfma_f32_16x16x32_bf16 v[128:131], v[226:229], v[12:15], v[24:27]
	v_exp_f32_e32 v74, v74
	v_mfma_f32_16x16x32_bf16 v[132:135], v[226:229], v[20:23], v[28:31]
	v_exp_f32_e32 v75, v75
	ds_read_b128 v[226:229], v179 offset:25216
	s_waitcnt lgkmcnt(7)
	v_mfma_f32_16x16x32_bf16 v[104:107], v[198:201], v[8:11], v[104:107]
	v_exp_f32_e32 v80, v80
	v_exp_f32_e32 v81, v81
	v_mfma_f32_16x16x32_bf16 v[108:111], v[198:201], v[16:19], v[108:111]
	v_exp_f32_e32 v82, v82
	s_waitcnt lgkmcnt(6)
	v_mfma_f32_16x16x32_bf16 v[112:115], v[202:205], v[8:11], v[112:115]
	v_exp_f32_e32 v83, v83
	v_mfma_f32_16x16x32_bf16 v[116:119], v[202:205], v[16:19], v[116:119]
	v_exp_f32_e32 v76, v76
	s_waitcnt lgkmcnt(5)
	v_mfma_f32_16x16x32_bf16 v[120:123], v[206:209], v[8:11], v[120:123]
	v_exp_f32_e32 v77, v77
	v_mfma_f32_16x16x32_bf16 v[124:127], v[206:209], v[16:19], v[124:127]
	v_exp_f32_e32 v78, v78
	v_exp_f32_e32 v79, v79
	s_waitcnt lgkmcnt(4)
	v_mfma_f32_16x16x32_bf16 v[128:131], v[210:213], v[8:11], v[128:131]
	v_exp_f32_e32 v84, v84
	v_mfma_f32_16x16x32_bf16 v[132:135], v[210:213], v[16:19], v[132:135]
	v_exp_f32_e32 v85, v85
	s_waitcnt lgkmcnt(3)
	v_mfma_f32_16x16x32_bf16 v[104:107], v[214:217], v[4:7], v[104:107]
	v_exp_f32_e32 v86, v86
	v_mfma_f32_16x16x32_bf16 v[108:111], v[214:217], v[0:3], v[108:111]
	v_exp_f32_e32 v87, v87
	s_waitcnt lgkmcnt(2)
	v_mfma_f32_16x16x32_bf16 v[112:115], v[218:221], v[4:7], v[112:115]
	v_cvt_pk_bf16_f32 v136, v72, v73
	v_cvt_pk_bf16_f32 v137, v74, v75
	v_mfma_f32_16x16x32_bf16 v[116:119], v[218:221], v[0:3], v[116:119]
	v_cvt_pk_bf16_f32 v138, v80, v81
	s_waitcnt lgkmcnt(1)
	v_mfma_f32_16x16x32_bf16 v[120:123], v[222:225], v[4:7], v[120:123]
	v_cvt_pk_bf16_f32 v139, v82, v83
	v_mfma_f32_16x16x32_bf16 v[124:127], v[222:225], v[0:3], v[124:127]
	v_cvt_pk_bf16_f32 v140, v76, v77
	s_waitcnt lgkmcnt(0)
	v_mfma_f32_16x16x32_bf16 v[128:131], v[226:229], v[4:7], v[128:131]
	v_cvt_pk_bf16_f32 v141, v78, v79
	v_mfma_f32_16x16x32_bf16 v[132:135], v[226:229], v[0:3], v[132:135]
	v_cvt_pk_bf16_f32 v142, v84, v85
	v_cvt_pk_bf16_f32 v143, v86, v87
	s_waitcnt lgkmcnt(0)
	s_barrier
	s_mov_b32 s18, s15
	s_mov_b32 s15, s12
	s_mov_b32 s12, s9
	s_mov_b32 s9, s18
	s_add_i32 s13, s13, 1
	s_cmp_lg_u32 s13, 16
	s_cbranch_scc1 .Lattn_b_loop
	global_load_dwordx4 v[230:233], v[164:165], off
	global_load_dwordx4 v[234:237], v[166:167], off
	global_load_dwordx4 v[238:241], v[168:169], off
	global_load_dwordx4 v[242:245], v[170:171], off
	global_load_dwordx4 v[246:249], v[172:173], off
	v_lshl_add_u64 v[164:165], v[164:165], 0, s[26:27]
	v_lshl_add_u64 v[166:167], v[166:167], 0, s[26:27]
	v_lshl_add_u64 v[168:169], v[168:169], 0, s[16:17]
	v_lshl_add_u64 v[170:171], v[170:171], 0, s[16:17]
	v_lshl_add_u64 v[172:173], v[172:173], 0, s[16:17]
	v_add_u32_e32 v184, s9, v159
	v_add_u32_e32 v185, s9, v161
	v_add_u32_e32 v186, s9, v163
	v_add_u32_e32 v187, s9, v160
	v_add_u32_e32 v188, s9, v162
	v_add3_u32 v180, s15, v176, v177
	ds_read_b64 v[198:199], v180 offset:28672
	ds_read_b64 v[200:201], v180 offset:28704
	ds_read_b64 v[202:203], v180 offset:33024
	ds_read_b64 v[204:205], v180 offset:33056
	ds_read_b64 v[206:207], v180 offset:37376
	ds_read_b64 v[208:209], v180 offset:37408
	ds_read_b64 v[210:211], v180 offset:41728
	ds_read_b64 v[212:213], v180 offset:41760
	ds_read_b64 v[214:215], v180 offset:28736
	ds_read_b64 v[216:217], v180 offset:28768
	ds_read_b64 v[218:219], v180 offset:33088
	ds_read_b64 v[220:221], v180 offset:33120
	ds_read_b64 v[222:223], v180 offset:37440
	ds_read_b64 v[224:225], v180 offset:37472
	ds_read_b64 v[226:227], v180 offset:41792
	ds_read_b64 v[228:229], v180 offset:41824
	v_mfma_f32_16x16x32_bf16 v[68:71], v[152:155], v[136:139], v[68:71]
	v_exp_f32_e32 v88, v88
	v_exp_f32_e32 v89, v89
	v_mfma_f32_16x16x32_bf16 v[56:59], v[152:155], v[140:143], v[56:59]
	v_exp_f32_e32 v90, v90
	v_exp_f32_e32 v91, v91
	s_waitcnt lgkmcnt(8)
; DEV float ex2(float x) { return __builtin_amdgcn_exp2f(x); }
; DEV void attn_item(const Params& p, int bl, int head, int q0, int nkeys, char* smem, int tid) {
;     ...
; #pragma unroll
;       for (int kk = 0; kk < 2; ++kk) {
;         bf16x8 pb[2];
; #pragma unroll
;         for (int qt = 0; qt < 2; ++qt) {
;           const float e0 = ex2(s[2 * kk][qt][0]), e1 = ex2(s[2 * kk][qt][1]), e2 = ex2(s[2 * kk][qt][2]), e3 = ex2(s[2 * kk][qt][3]);
;           const float e4 = ex2(s[2 * kk + 1][qt][0]), e5 = ex2(s[2 * kk + 1][qt][1]), e6 = ex2(s[2 * kk + 1][qt][2]), e7 = ex2(s[2 * kk + 1][qt][3]);
;           u32x4 cw = {pack2(e0, e1), pack2(e2, e3), pack2(e4, e5), pack2(e6, e7)};
;           pb[qt] = __builtin_bit_cast(bf16x8, cw);
;         }
;         lacc[0] = __builtin_amdgcn_mfma_f32_16x16x32_bf16(ones, pb[0], lacc[0], 0, 0, 0);
;         lacc[1] = __builtin_amdgcn_mfma_f32_16x16x32_bf16(ones, pb[1], lacc[1], 0, 0, 0);
; #pragma unroll
;         for (int dvf = 0; dvf < 4; ++dvf) {
;           const char* vp = vb + (dvf * 16 + fr) * VROW + (hh * 64 + kk * 32 + fq * 4) * 2;
;           const uint2 h0 = *(const uint2*)vp, h1 = *(const uint2*)(vp + 32);
;           u32x4 vw = {h0.x, h0.y, h1.x, h1.y};
;           const bf16x8 va = __builtin_bit_cast(bf16x8, vw);
;           o[dvf][0] = __builtin_amdgcn_mfma_f32_16x16x32_bf16(va, pb[0], o[dvf][0], 0, 0, 0);
;           o[dvf][1] = __builtin_amdgcn_mfma_f32_16x16x32_bf16(va, pb[1], o[dvf][1], 0, 0, 0);
;         }
	v_mfma_f32_16x16x32_bf16 v[32:35], v[198:201], v[136:139], v[32:35]
	v_exp_f32_e32 v96, v96
	v_exp_f32_e32 v97, v97
	v_mfma_f32_16x16x32_bf16 v[36:39], v[198:201], v[140:143], v[36:39]
	v_exp_f32_e32 v98, v98
	v_exp_f32_e32 v99, v99
	v_exp_f32_e32 v92, v92
	v_mfma_f32_16x16x32_bf16 v[40:43], v[202:205], v[136:139], v[40:43]
	v_exp_f32_e32 v93, v93
	v_exp_f32_e32 v94, v94
	v_mfma_f32_16x16x32_bf16 v[60:63], v[202:205], v[140:143], v[60:63]
	v_exp_f32_e32 v95, v95
	v_exp_f32_e32 v100, v100
	v_exp_f32_e32 v101, v101
	v_mfma_f32_16x16x32_bf16 v[44:47], v[206:209], v[136:139], v[44:47]
	v_exp_f32_e32 v102, v102
	v_exp_f32_e32 v103, v103
	v_mfma_f32_16x16x32_bf16 v[64:67], v[206:209], v[140:143], v[64:67]
	v_cvt_pk_bf16_f32 v144, v88, v89
	v_cvt_pk_bf16_f32 v145, v90, v91
	v_cvt_pk_bf16_f32 v146, v96, v97
	v_mfma_f32_16x16x32_bf16 v[48:51], v[210:213], v[136:139], v[48:51]
	v_cvt_pk_bf16_f32 v147, v98, v99
	v_cvt_pk_bf16_f32 v148, v92, v93
	v_mfma_f32_16x16x32_bf16 v[52:55], v[210:213], v[140:143], v[52:55]
	v_cvt_pk_bf16_f32 v149, v94, v95
	v_cvt_pk_bf16_f32 v150, v100, v101
	v_cvt_pk_bf16_f32 v151, v102, v103
	ds_read_b64 v[198:199], v180 offset:28800
	ds_read_b64 v[200:201], v180 offset:28832
	ds_read_b64 v[202:203], v180 offset:33152
	ds_read_b64 v[204:205], v180 offset:33184
	ds_read_b64 v[206:207], v180 offset:37504
	ds_read_b64 v[208:209], v180 offset:37536
	ds_read_b64 v[210:211], v180 offset:41856
	ds_read_b64 v[212:213], v180 offset:41888
	s_nop 1
	v_mfma_f32_16x16x32_bf16 v[68:71], v[152:155], v[144:147], v[68:71]
	v_exp_f32_e32 v104, v104
	v_exp_f32_e32 v105, v105
	v_mfma_f32_16x16x32_bf16 v[56:59], v[152:155], v[148:151], v[56:59]
	v_exp_f32_e32 v106, v106
	v_exp_f32_e32 v107, v107
	s_waitcnt lgkmcnt(8)
	v_mfma_f32_16x16x32_bf16 v[32:35], v[214:217], v[144:147], v[32:35]
	v_exp_f32_e32 v112, v112
	v_exp_f32_e32 v113, v113
	v_mfma_f32_16x16x32_bf16 v[36:39], v[214:217], v[148:151], v[36:39]
	v_exp_f32_e32 v114, v114
	v_exp_f32_e32 v115, v115
	v_exp_f32_e32 v108, v108
	v_mfma_f32_16x16x32_bf16 v[40:43], v[218:221], v[144:147], v[40:43]
	v_exp_f32_e32 v109, v109
	v_exp_f32_e32 v110, v110
	v_mfma_f32_16x16x32_bf16 v[60:63], v[218:221], v[148:151], v[60:63]
	v_exp_f32_e32 v111, v111
	v_exp_f32_e32 v116, v116
	v_exp_f32_e32 v117, v117
	v_mfma_f32_16x16x32_bf16 v[44:47], v[222:225], v[144:147], v[44:47]
	v_exp_f32_e32 v118, v118
	v_exp_f32_e32 v119, v119
	v_mfma_f32_16x16x32_bf16 v[64:67], v[222:225], v[148:151], v[64:67]
	v_cvt_pk_bf16_f32 v136, v104, v105
	v_cvt_pk_bf16_f32 v137, v106, v107
	v_cvt_pk_bf16_f32 v138, v112, v113
	v_mfma_f32_16x16x32_bf16 v[48:51], v[226:229], v[144:147], v[48:51]
	v_cvt_pk_bf16_f32 v139, v114, v115
	v_cvt_pk_bf16_f32 v140, v108, v109
	v_mfma_f32_16x16x32_bf16 v[52:55], v[226:229], v[148:151], v[52:55]
	v_cvt_pk_bf16_f32 v141, v110, v111
	v_cvt_pk_bf16_f32 v142, v116, v117
	v_cvt_pk_bf16_f32 v143, v118, v119
	ds_read_b64 v[214:215], v180 offset:28864
	ds_read_b64 v[216:217], v180 offset:28896
	ds_read_b64 v[218:219], v180 offset:33216
	ds_read_b64 v[220:221], v180 offset:33248
	ds_read_b64 v[222:223], v180 offset:37568
	ds_read_b64 v[224:225], v180 offset:37600
	ds_read_b64 v[226:227], v180 offset:41920
	ds_read_b64 v[228:229], v180 offset:41952
	s_nop 1
	v_mfma_f32_16x16x32_bf16 v[68:71], v[152:155], v[136:139], v[68:71]
	v_exp_f32_e32 v120, v120
	v_exp_f32_e32 v121, v121
	v_mfma_f32_16x16x32_bf16 v[56:59], v[152:155], v[140:143], v[56:59]
	v_exp_f32_e32 v122, v122
	v_exp_f32_e32 v123, v123
	s_waitcnt lgkmcnt(8)
	v_mfma_f32_16x16x32_bf16 v[32:35], v[198:201], v[136:139], v[32:35]
	v_exp_f32_e32 v128, v128
	v_exp_f32_e32 v129, v129
	v_mfma_f32_16x16x32_bf16 v[36:39], v[198:201], v[140:143], v[36:39]
	v_exp_f32_e32 v130, v130
	v_exp_f32_e32 v131, v131
	v_exp_f32_e32 v124, v124
	v_mfma_f32_16x16x32_bf16 v[40:43], v[202:205], v[136:139], v[40:43]
	v_exp_f32_e32 v125, v125
	v_exp_f32_e32 v126, v126
	v_mfma_f32_16x16x32_bf16 v[60:63], v[202:205], v[140:143], v[60:63]
	v_exp_f32_e32 v127, v127
	v_exp_f32_e32 v132, v132
	v_exp_f32_e32 v133, v133
	v_mfma_f32_16x16x32_bf16 v[44:47], v[206:209], v[136:139], v[44:47]
	v_exp_f32_e32 v134, v134
	v_exp_f32_e32 v135, v135
	v_mfma_f32_16x16x32_bf16 v[64:67], v[206:209], v[140:143], v[64:67]
	v_cvt_pk_bf16_f32 v144, v120, v121
	v_cvt_pk_bf16_f32 v145, v122, v123
	v_cvt_pk_bf16_f32 v146, v128, v129
	v_mfma_f32_16x16x32_bf16 v[48:51], v[210:213], v[136:139], v[48:51]
	v_cvt_pk_bf16_f32 v147, v130, v131
	v_cvt_pk_bf16_f32 v148, v124, v125
	v_mfma_f32_16x16x32_bf16 v[52:55], v[210:213], v[140:143], v[52:55]
	v_cvt_pk_bf16_f32 v149, v126, v127
	v_cvt_pk_bf16_f32 v150, v132, v133
	v_cvt_pk_bf16_f32 v151, v134, v135
	s_nop 1
	v_mfma_f32_16x16x32_bf16 v[68:71], v[152:155], v[144:147], v[68:71]
	v_mfma_f32_16x16x32_bf16 v[56:59], v[152:155], v[148:151], v[56:59]
	s_waitcnt lgkmcnt(0)
	v_mfma_f32_16x16x32_bf16 v[32:35], v[214:217], v[144:147], v[32:35]
	v_mfma_f32_16x16x32_bf16 v[36:39], v[214:217], v[148:151], v[36:39]
	v_mfma_f32_16x16x32_bf16 v[40:43], v[218:221], v[144:147], v[40:43]
	v_mfma_f32_16x16x32_bf16 v[60:63], v[218:221], v[148:151], v[60:63]
	v_mfma_f32_16x16x32_bf16 v[44:47], v[222:225], v[144:147], v[44:47]
	v_mfma_f32_16x16x32_bf16 v[64:67], v[222:225], v[148:151], v[64:67]
	v_mfma_f32_16x16x32_bf16 v[48:51], v[226:229], v[144:147], v[48:51]
	v_mfma_f32_16x16x32_bf16 v[52:55], v[226:229], v[148:151], v[52:55]
	s_waitcnt vmcnt(0)
; DEV float ex2(float x) { return __builtin_amdgcn_exp2f(x); }
; DEV void attn_item(const Params& p, int bl, int head, int q0, int nkeys, char* smem, int tid) {
;     ...
;     for (int hh = 0; hh < 2; ++hh) {
;       f32x4 s[4][2];
; #pragma unroll
;       for (int kf = 0; kf < 4; ++kf) {
; #pragma unroll
;         for (int ks = 0; ks < 3; ++ks) {
;           bf16x8 a = *(const bf16x8*)(kb + (hh * 64 + kf * 16 + fr) * KROW + ks * 64 + fq * 16);
;           s[kf][0] = __builtin_amdgcn_mfma_f32_16x16x32_bf16(a, qf[0][ks], ks == 0 ? negm[0] : s[kf][0], 0, 0, 0);
;           s[kf][1] = __builtin_amdgcn_mfma_f32_16x16x32_bf16(a, qf[1][ks], ks == 0 ? negm[1] : s[kf][1], 0, 0, 0);
;         }
;       }
; #pragma unroll
;       for (int kk = 0; kk < 2; ++kk) {
;         bf16x8 pb[2];
; #pragma unroll
;         for (int qt = 0; qt < 2; ++qt) {
;           const float e0 = ex2(s[2 * kk][qt][0]), e1 = ex2(s[2 * kk][qt][1]), e2 = ex2(s[2 * kk][qt][2]), e3 = ex2(s[2 * kk][qt][3]);
;           const float e4 = ex2(s[2 * kk + 1][qt][0]), e5 = ex2(s[2 * kk + 1][qt][1]), e6 = ex2(s[2 * kk + 1][qt][2]), e7 = ex2(s[2 * kk + 1][qt][3]);
;           u32x4 cw = {pack2(e0, e1), pack2(e2, e3), pack2(e4, e5), pack2(e6, e7)};
;           pb[qt] = __builtin_bit_cast(bf16x8, cw);
;         }
;     ...
;     if (t + 1 < nt) {
;       char* nb = smem + ((t + 1) & 1) * ASTG;
; #pragma unroll
;       for (int i = 0; i < 3; ++i) *(u32x4*)(nb + koff[i]) = kr[i];
; #pragma unroll
;       for (int i = 0; i < 2; ++i) *(u32x4*)(nb + KBYTES + voffl[i]) = vr[i];
;     }
	ds_write_b128 v184, v[238:241]
	ds_write_b128 v185, v[242:245]
	ds_write_b128 v186, v[246:249]
	ds_write_b128 v187, v[230:233] offset:26624
	ds_write_b128 v188, v[234:237] offset:26624
	v_add3_u32 v179, s12, v156, v181
	ds_read_b128 v[198:201], v179
	ds_read_b128 v[202:205], v179 offset:3584
	ds_read_b128 v[206:209], v179 offset:7168
	ds_read_b128 v[210:213], v179 offset:10752
	ds_read_b128 v[214:217], v179 offset:64
	ds_read_b128 v[218:221], v179 offset:3648
	ds_read_b128 v[222:225], v179 offset:7232
	ds_read_b128 v[226:229], v179 offset:10816
	s_waitcnt lgkmcnt(7)
	v_mfma_f32_16x16x32_bf16 v[72:75], v[198:201], v[12:15], v[24:27]
	v_mfma_f32_16x16x32_bf16 v[76:79], v[198:201], v[20:23], v[28:31]
	ds_read_b128 v[198:201], v179 offset:128
	s_waitcnt lgkmcnt(7)
	v_mfma_f32_16x16x32_bf16 v[80:83], v[202:205], v[12:15], v[24:27]
	v_mfma_f32_16x16x32_bf16 v[84:87], v[202:205], v[20:23], v[28:31]
	ds_read_b128 v[202:205], v179 offset:3712
	s_waitcnt lgkmcnt(7)
	v_mfma_f32_16x16x32_bf16 v[88:91], v[206:209], v[12:15], v[24:27]
	v_mfma_f32_16x16x32_bf16 v[92:95], v[206:209], v[20:23], v[28:31]
	ds_read_b128 v[206:209], v179 offset:7296
	s_waitcnt lgkmcnt(7)
	v_mfma_f32_16x16x32_bf16 v[96:99], v[210:213], v[12:15], v[24:27]
	v_mfma_f32_16x16x32_bf16 v[100:103], v[210:213], v[20:23], v[28:31]
	ds_read_b128 v[210:213], v179 offset:10880
	s_waitcnt lgkmcnt(7)
	v_mfma_f32_16x16x32_bf16 v[72:75], v[214:217], v[8:11], v[72:75]
	v_mfma_f32_16x16x32_bf16 v[76:79], v[214:217], v[16:19], v[76:79]
	ds_read_b128 v[214:217], v179 offset:14336
	s_waitcnt lgkmcnt(7)
	v_mfma_f32_16x16x32_bf16 v[80:83], v[218:221], v[8:11], v[80:83]
	v_mfma_f32_16x16x32_bf16 v[84:87], v[218:221], v[16:19], v[84:87]
	ds_read_b128 v[218:221], v179 offset:17920
	s_waitcnt lgkmcnt(7)
	v_mfma_f32_16x16x32_bf16 v[88:91], v[222:225], v[8:11], v[88:91]
	v_mfma_f32_16x16x32_bf16 v[92:95], v[222:225], v[16:19], v[92:95]
	ds_read_b128 v[222:225], v179 offset:21504
	s_waitcnt lgkmcnt(7)
	v_mfma_f32_16x16x32_bf16 v[96:99], v[226:229], v[8:11], v[96:99]
	v_mfma_f32_16x16x32_bf16 v[100:103], v[226:229], v[16:19], v[100:103]
	ds_read_b128 v[226:229], v179 offset:25088
	s_waitcnt lgkmcnt(7)
	v_mfma_f32_16x16x32_bf16 v[72:75], v[198:201], v[4:7], v[72:75]
	v_mfma_f32_16x16x32_bf16 v[76:79], v[198:201], v[0:3], v[76:79]
	ds_read_b128 v[198:201], v179 offset:14400
	s_waitcnt lgkmcnt(7)
	v_mfma_f32_16x16x32_bf16 v[80:83], v[202:205], v[4:7], v[80:83]
	v_mfma_f32_16x16x32_bf16 v[84:87], v[202:205], v[0:3], v[84:87]
	ds_read_b128 v[202:205], v179 offset:17984
	s_waitcnt lgkmcnt(7)
	v_mfma_f32_16x16x32_bf16 v[88:91], v[206:209], v[4:7], v[88:91]
	v_mfma_f32_16x16x32_bf16 v[92:95], v[206:209], v[0:3], v[92:95]
	ds_read_b128 v[206:209], v179 offset:21568
	s_waitcnt lgkmcnt(7)
	v_mfma_f32_16x16x32_bf16 v[96:99], v[210:213], v[4:7], v[96:99]
	v_mfma_f32_16x16x32_bf16 v[100:103], v[210:213], v[0:3], v[100:103]
	ds_read_b128 v[210:213], v179 offset:25152
	s_waitcnt lgkmcnt(7)
	v_mfma_f32_16x16x32_bf16 v[104:107], v[214:217], v[12:15], v[24:27]
	v_mfma_f32_16x16x32_bf16 v[108:111], v[214:217], v[20:23], v[28:31]
	ds_read_b128 v[214:217], v179 offset:14464
	s_waitcnt lgkmcnt(7)
	v_mfma_f32_16x16x32_bf16 v[112:115], v[218:221], v[12:15], v[24:27]
	v_mfma_f32_16x16x32_bf16 v[116:119], v[218:221], v[20:23], v[28:31]
	ds_read_b128 v[218:221], v179 offset:18048
	s_waitcnt lgkmcnt(7)
	v_mfma_f32_16x16x32_bf16 v[120:123], v[222:225], v[12:15], v[24:27]
	v_exp_f32_e32 v72, v72
	v_mfma_f32_16x16x32_bf16 v[124:127], v[222:225], v[20:23], v[28:31]
	v_exp_f32_e32 v73, v73
	ds_read_b128 v[222:225], v179 offset:21632
	s_waitcnt lgkmcnt(7)
	v_mfma_f32_16x16x32_bf16 v[128:131], v[226:229], v[12:15], v[24:27]
	v_exp_f32_e32 v74, v74
	v_mfma_f32_16x16x32_bf16 v[132:135], v[226:229], v[20:23], v[28:31]
	v_exp_f32_e32 v75, v75
	ds_read_b128 v[226:229], v179 offset:25216
	s_waitcnt lgkmcnt(7)
	v_mfma_f32_16x16x32_bf16 v[104:107], v[198:201], v[8:11], v[104:107]
	v_exp_f32_e32 v80, v80
	v_exp_f32_e32 v81, v81
	v_mfma_f32_16x16x32_bf16 v[108:111], v[198:201], v[16:19], v[108:111]
	v_exp_f32_e32 v82, v82
	s_waitcnt lgkmcnt(6)
	v_mfma_f32_16x16x32_bf16 v[112:115], v[202:205], v[8:11], v[112:115]
	v_exp_f32_e32 v83, v83
	v_mfma_f32_16x16x32_bf16 v[116:119], v[202:205], v[16:19], v[116:119]
	v_exp_f32_e32 v76, v76
	s_waitcnt lgkmcnt(5)
	v_mfma_f32_16x16x32_bf16 v[120:123], v[206:209], v[8:11], v[120:123]
	v_exp_f32_e32 v77, v77
	v_mfma_f32_16x16x32_bf16 v[124:127], v[206:209], v[16:19], v[124:127]
	v_exp_f32_e32 v78, v78
	v_exp_f32_e32 v79, v79
	s_waitcnt lgkmcnt(4)
	v_mfma_f32_16x16x32_bf16 v[128:131], v[210:213], v[8:11], v[128:131]
	v_exp_f32_e32 v84, v84
	v_mfma_f32_16x16x32_bf16 v[132:135], v[210:213], v[16:19], v[132:135]
	v_exp_f32_e32 v85, v85
	s_waitcnt lgkmcnt(3)
	v_mfma_f32_16x16x32_bf16 v[104:107], v[214:217], v[4:7], v[104:107]
	v_exp_f32_e32 v86, v86
	v_mfma_f32_16x16x32_bf16 v[108:111], v[214:217], v[0:3], v[108:111]
	v_exp_f32_e32 v87, v87
	s_waitcnt lgkmcnt(2)
	v_mfma_f32_16x16x32_bf16 v[112:115], v[218:221], v[4:7], v[112:115]
	v_cvt_pk_bf16_f32 v136, v72, v73
	v_cvt_pk_bf16_f32 v137, v74, v75
	v_mfma_f32_16x16x32_bf16 v[116:119], v[218:221], v[0:3], v[116:119]
	v_cvt_pk_bf16_f32 v138, v80, v81
	s_waitcnt lgkmcnt(1)
	v_mfma_f32_16x16x32_bf16 v[120:123], v[222:225], v[4:7], v[120:123]
	v_cvt_pk_bf16_f32 v139, v82, v83
	v_mfma_f32_16x16x32_bf16 v[124:127], v[222:225], v[0:3], v[124:127]
	v_cvt_pk_bf16_f32 v140, v76, v77
	s_waitcnt lgkmcnt(0)
	v_mfma_f32_16x16x32_bf16 v[128:131], v[226:229], v[4:7], v[128:131]
	v_cvt_pk_bf16_f32 v141, v78, v79
	v_mfma_f32_16x16x32_bf16 v[132:135], v[226:229], v[0:3], v[132:135]
	v_cvt_pk_bf16_f32 v142, v84, v85
	v_cvt_pk_bf16_f32 v143, v86, v87
	s_waitcnt lgkmcnt(0)
	s_barrier
; DEV float ex2(float x) { return __builtin_amdgcn_exp2f(x); }
; DEV void attn_item(const Params& p, int bl, int head, int q0, int nkeys, char* smem, int tid) {
;     ...
; #pragma unroll
;       for (int kk = 0; kk < 2; ++kk) {
;         bf16x8 pb[2];
; #pragma unroll
;         for (int qt = 0; qt < 2; ++qt) {
;           const float e0 = ex2(s[2 * kk][qt][0]), e1 = ex2(s[2 * kk][qt][1]), e2 = ex2(s[2 * kk][qt][2]), e3 = ex2(s[2 * kk][qt][3]);
;           const float e4 = ex2(s[2 * kk + 1][qt][0]), e5 = ex2(s[2 * kk + 1][qt][1]), e6 = ex2(s[2 * kk + 1][qt][2]), e7 = ex2(s[2 * kk + 1][qt][3]);
;           u32x4 cw = {pack2(e0, e1), pack2(e2, e3), pack2(e4, e5), pack2(e6, e7)};
;           pb[qt] = __builtin_bit_cast(bf16x8, cw);
;         }
;         lacc[0] = __builtin_amdgcn_mfma_f32_16x16x32_bf16(ones, pb[0], lacc[0], 0, 0, 0);
;         lacc[1] = __builtin_amdgcn_mfma_f32_16x16x32_bf16(ones, pb[1], lacc[1], 0, 0, 0);
; #pragma unroll
;         for (int dvf = 0; dvf < 4; ++dvf) {
;           const char* vp = vb + (dvf * 16 + fr) * VROW + (hh * 64 + kk * 32 + fq * 4) * 2;
;           const uint2 h0 = *(const uint2*)vp, h1 = *(const uint2*)(vp + 32);
;           u32x4 vw = {h0.x, h0.y, h1.x, h1.y};
;           const bf16x8 va = __builtin_bit_cast(bf16x8, vw);
;           o[dvf][0] = __builtin_amdgcn_mfma_f32_16x16x32_bf16(va, pb[0], o[dvf][0], 0, 0, 0);
;           o[dvf][1] = __builtin_amdgcn_mfma_f32_16x16x32_bf16(va, pb[1], o[dvf][1], 0, 0, 0);
;         }
	s_mov_b32 s18, s15
	s_mov_b32 s15, s12
	s_mov_b32 s12, s9
	s_mov_b32 s9, s18
	s_add_i32 s13, s13, 1
	v_add3_u32 v180, s15, v176, v177
	ds_read_b64 v[198:199], v180 offset:28672
	ds_read_b64 v[200:201], v180 offset:28704
	ds_read_b64 v[202:203], v180 offset:33024
	ds_read_b64 v[204:205], v180 offset:33056
	ds_read_b64 v[206:207], v180 offset:37376
	ds_read_b64 v[208:209], v180 offset:37408
	ds_read_b64 v[210:211], v180 offset:41728
	ds_read_b64 v[212:213], v180 offset:41760
	ds_read_b64 v[214:215], v180 offset:28736
	ds_read_b64 v[216:217], v180 offset:28768
	ds_read_b64 v[218:219], v180 offset:33088
	ds_read_b64 v[220:221], v180 offset:33120
	ds_read_b64 v[222:223], v180 offset:37440
	ds_read_b64 v[224:225], v180 offset:37472
	ds_read_b64 v[226:227], v180 offset:41792
	ds_read_b64 v[228:229], v180 offset:41824
	v_mfma_f32_16x16x32_bf16 v[68:71], v[152:155], v[136:139], v[68:71]
	v_exp_f32_e32 v88, v88
	v_exp_f32_e32 v89, v89
	v_mfma_f32_16x16x32_bf16 v[56:59], v[152:155], v[140:143], v[56:59]
	v_exp_f32_e32 v90, v90
	v_exp_f32_e32 v91, v91
	s_waitcnt lgkmcnt(8)
	v_mfma_f32_16x16x32_bf16 v[32:35], v[198:201], v[136:139], v[32:35]
	v_exp_f32_e32 v96, v96
	v_exp_f32_e32 v97, v97
	v_mfma_f32_16x16x32_bf16 v[36:39], v[198:201], v[140:143], v[36:39]
	v_exp_f32_e32 v98, v98
	v_exp_f32_e32 v99, v99
	v_exp_f32_e32 v92, v92
	v_mfma_f32_16x16x32_bf16 v[40:43], v[202:205], v[136:139], v[40:43]
	v_exp_f32_e32 v93, v93
	v_exp_f32_e32 v94, v94
	v_mfma_f32_16x16x32_bf16 v[60:63], v[202:205], v[140:143], v[60:63]
	v_exp_f32_e32 v95, v95
	v_exp_f32_e32 v100, v100
	v_exp_f32_e32 v101, v101
	v_mfma_f32_16x16x32_bf16 v[44:47], v[206:209], v[136:139], v[44:47]
	v_exp_f32_e32 v102, v102
	v_exp_f32_e32 v103, v103
	v_mfma_f32_16x16x32_bf16 v[64:67], v[206:209], v[140:143], v[64:67]
	v_cvt_pk_bf16_f32 v144, v88, v89
	v_cvt_pk_bf16_f32 v145, v90, v91
	v_cvt_pk_bf16_f32 v146, v96, v97
	v_mfma_f32_16x16x32_bf16 v[48:51], v[210:213], v[136:139], v[48:51]
	v_cvt_pk_bf16_f32 v147, v98, v99
	v_cvt_pk_bf16_f32 v148, v92, v93
	v_mfma_f32_16x16x32_bf16 v[52:55], v[210:213], v[140:143], v[52:55]
	v_cvt_pk_bf16_f32 v149, v94, v95
	v_cvt_pk_bf16_f32 v150, v100, v101
	v_cvt_pk_bf16_f32 v151, v102, v103
	ds_read_b64 v[198:199], v180 offset:28800
	ds_read_b64 v[200:201], v180 offset:28832
	ds_read_b64 v[202:203], v180 offset:33152
	ds_read_b64 v[204:205], v180 offset:33184
	ds_read_b64 v[206:207], v180 offset:37504
	ds_read_b64 v[208:209], v180 offset:37536
	ds_read_b64 v[210:211], v180 offset:41856
	ds_read_b64 v[212:213], v180 offset:41888
	s_nop 1
	v_mfma_f32_16x16x32_bf16 v[68:71], v[152:155], v[144:147], v[68:71]
	v_exp_f32_e32 v104, v104
	v_exp_f32_e32 v105, v105
	v_mfma_f32_16x16x32_bf16 v[56:59], v[152:155], v[148:151], v[56:59]
	v_exp_f32_e32 v106, v106
	v_exp_f32_e32 v107, v107
	s_waitcnt lgkmcnt(8)
	v_mfma_f32_16x16x32_bf16 v[32:35], v[214:217], v[144:147], v[32:35]
	v_exp_f32_e32 v112, v112
	v_exp_f32_e32 v113, v113
	v_mfma_f32_16x16x32_bf16 v[36:39], v[214:217], v[148:151], v[36:39]
	v_exp_f32_e32 v114, v114
	v_exp_f32_e32 v115, v115
	v_exp_f32_e32 v108, v108
	v_mfma_f32_16x16x32_bf16 v[40:43], v[218:221], v[144:147], v[40:43]
	v_exp_f32_e32 v109, v109
	v_exp_f32_e32 v110, v110
	v_mfma_f32_16x16x32_bf16 v[60:63], v[218:221], v[148:151], v[60:63]
	v_exp_f32_e32 v111, v111
	v_exp_f32_e32 v116, v116
	v_exp_f32_e32 v117, v117
	v_mfma_f32_16x16x32_bf16 v[44:47], v[222:225], v[144:147], v[44:47]
	v_exp_f32_e32 v118, v118
	v_exp_f32_e32 v119, v119
	v_mfma_f32_16x16x32_bf16 v[64:67], v[222:225], v[148:151], v[64:67]
	v_cvt_pk_bf16_f32 v136, v104, v105
	v_cvt_pk_bf16_f32 v137, v106, v107
	v_cvt_pk_bf16_f32 v138, v112, v113
	v_mfma_f32_16x16x32_bf16 v[48:51], v[226:229], v[144:147], v[48:51]
	v_cvt_pk_bf16_f32 v139, v114, v115
	v_cvt_pk_bf16_f32 v140, v108, v109
	v_mfma_f32_16x16x32_bf16 v[52:55], v[226:229], v[148:151], v[52:55]
	v_cvt_pk_bf16_f32 v141, v110, v111
	v_cvt_pk_bf16_f32 v142, v116, v117
	v_cvt_pk_bf16_f32 v143, v118, v119
	ds_read_b64 v[214:215], v180 offset:28864
	ds_read_b64 v[216:217], v180 offset:28896
	ds_read_b64 v[218:219], v180 offset:33216
	ds_read_b64 v[220:221], v180 offset:33248
	ds_read_b64 v[222:223], v180 offset:37568
	ds_read_b64 v[224:225], v180 offset:37600
	ds_read_b64 v[226:227], v180 offset:41920
	ds_read_b64 v[228:229], v180 offset:41952
	s_nop 1
	v_mfma_f32_16x16x32_bf16 v[68:71], v[152:155], v[136:139], v[68:71]
	v_exp_f32_e32 v120, v120
	v_exp_f32_e32 v121, v121
	v_mfma_f32_16x16x32_bf16 v[56:59], v[152:155], v[140:143], v[56:59]
	v_exp_f32_e32 v122, v122
	v_exp_f32_e32 v123, v123
	s_waitcnt lgkmcnt(8)
	v_mfma_f32_16x16x32_bf16 v[32:35], v[198:201], v[136:139], v[32:35]
	v_exp_f32_e32 v128, v128
	v_exp_f32_e32 v129, v129
	v_mfma_f32_16x16x32_bf16 v[36:39], v[198:201], v[140:143], v[36:39]
	v_exp_f32_e32 v130, v130
	v_exp_f32_e32 v131, v131
	v_exp_f32_e32 v124, v124
	v_mfma_f32_16x16x32_bf16 v[40:43], v[202:205], v[136:139], v[40:43]
	v_exp_f32_e32 v125, v125
	v_exp_f32_e32 v126, v126
	v_mfma_f32_16x16x32_bf16 v[60:63], v[202:205], v[140:143], v[60:63]
	v_exp_f32_e32 v127, v127
	v_exp_f32_e32 v132, v132
	v_exp_f32_e32 v133, v133
	v_mfma_f32_16x16x32_bf16 v[44:47], v[206:209], v[136:139], v[44:47]
	v_exp_f32_e32 v134, v134
	v_exp_f32_e32 v135, v135
	v_mfma_f32_16x16x32_bf16 v[64:67], v[206:209], v[140:143], v[64:67]
	v_cvt_pk_bf16_f32 v144, v120, v121
	v_cvt_pk_bf16_f32 v145, v122, v123
	v_cvt_pk_bf16_f32 v146, v128, v129
	v_mfma_f32_16x16x32_bf16 v[48:51], v[210:213], v[136:139], v[48:51]
	v_cvt_pk_bf16_f32 v147, v130, v131
	v_cvt_pk_bf16_f32 v148, v124, v125
	v_mfma_f32_16x16x32_bf16 v[52:55], v[210:213], v[140:143], v[52:55]
	v_cvt_pk_bf16_f32 v149, v126, v127
	v_cvt_pk_bf16_f32 v150, v132, v133
	v_cvt_pk_bf16_f32 v151, v134, v135
	s_nop 1
	v_mfma_f32_16x16x32_bf16 v[68:71], v[152:155], v[144:147], v[68:71]
	v_mfma_f32_16x16x32_bf16 v[56:59], v[152:155], v[148:151], v[56:59]
	s_waitcnt lgkmcnt(0)
	v_mfma_f32_16x16x32_bf16 v[32:35], v[214:217], v[144:147], v[32:35]
	v_mfma_f32_16x16x32_bf16 v[36:39], v[214:217], v[148:151], v[36:39]
	v_mfma_f32_16x16x32_bf16 v[40:43], v[218:221], v[144:147], v[40:43]
	v_mfma_f32_16x16x32_bf16 v[60:63], v[218:221], v[148:151], v[60:63]
	v_mfma_f32_16x16x32_bf16 v[44:47], v[222:225], v[144:147], v[44:47]
	v_mfma_f32_16x16x32_bf16 v[64:67], v[222:225], v[148:151], v[64:67]
	v_mfma_f32_16x16x32_bf16 v[48:51], v[226:229], v[144:147], v[48:51]
	v_mfma_f32_16x16x32_bf16 v[52:55], v[226:229], v[148:151], v[52:55]
	s_waitcnt lgkmcnt(0)
